# v082 + GEMM load blocks issue the LDS-DMA prefetch group ahead of the operand ds_reads (more lead time for the prefetch)
# speedup vs baseline: 1.0074x; 1.0074x over previous
; #define PG8_STAGE(bufoff, gbase, voff) do { _Pragma("unroll") for (int _i = 0; _i < 2; ++_i) \
;         __builtin_amdgcn_global_load_lds((const gunsigned*)((const gchar*)(gbase) + (voff)[_i]), (LAS unsigned*)(lds + (bufoff) + ldsw + _i * 8192), 16, 0, 0); } while (0)
; #define PG8_LDA(dst, b, h) do { _Pragma("unroll") for (int m = 0; m < 4; ++m) _Pragma("unroll") for (int k = 0; k < 2; ++k) dst[m][k] = *(const LAS bf16x8*)(lds + PG8_SA(b, h) + aoff + m * 2048 + k * 1024); } while (0)
; #define PG8_LDB(dst, b, h) do { _Pragma("unroll") for (int n = 0; n < 2; ++n) _Pragma("unroll") for (int k = 0; k < 2; ++k) dst[n][k] = *(const LAS bf16x8*)(lds + PG8_SB(b, h) + boff + n * 2048 + k * 1024); } while (0)
; #define PG8_MMA(ai, bj, At, Bt) do { __builtin_amdgcn_s_setprio(1); _Pragma("unroll") for (int m = 0; m < 4; ++m) _Pragma("unroll") for (int n = 0; n < 2; ++n) _Pragma("unroll") for (int k = 0; k < 2; ++k) \
;         acc[ai][bj][m][n] = __builtin_amdgcn_mfma_f32_16x16x32_bf16(Bt[n][k], At[m][k], acc[ai][bj][m][n], 0, 0, 0); __builtin_amdgcn_s_setprio(0); } while (0)
; #define PG8_WAIT_V(n) asm volatile("s_waitcnt vmcnt(" #n ")" ::: "memory")
; #define PG8_WAIT_L(n) asm volatile("s_waitcnt lgkmcnt(" #n ")" ::: "memory")
; #define PG8_BAR __builtin_amdgcn_s_barrier()
; #define PG8_SCHED __builtin_amdgcn_sched_barrier(0)
; template <class Epi, class Sched>
; __device__ __forceinline__ void gemm_phase(LAS unsigned char* lds, const int tid, const Gemm g, const Sched& S, const Epi& E) {
;     ...
;             const gchar* a1 = cA + (size_t)(t + 1) * kstep;
;             const gchar* a2 = last ? nA : cA + (size_t)(t + 2) * kstep; const gchar* b2 = last ? nB : cB + (size_t)(t + 2) * kstep;
;             const gchar* a3 = a2 + kstep; const gchar* b3 = b2 + kstep;
;             PG8_LDB(B0, 0, 0); PG8_LDB(B1, 0, 1); PG8_SCHED; PG8_LDA(At, 0, 0); PG8_STAGE(PG8_SA(1, 1), a1 + hstep, voffA);
;             PG8_WAIT_V(8); PG8_WAIT_L(0); PG8_BAR; PG8_MMA(0, 0, At, B0); PG8_MMA(0, 1, At, B1); PG8_BAR; PG8_SCHED;
;             PG8_LDA(At, 0, 1); PG8_STAGE(PG8_SB(0, 0), b2, voffB); PG8_STAGE(PG8_SB(0, 1), b2 + hstep, voffB); PG8_STAGE(PG8_SA(0, 0), a2, voffA);
;             PG8_WAIT_V(8); PG8_WAIT_L(0); PG8_BAR; PG8_MMA(1, 0, At, B0); PG8_MMA(1, 1, At, B1); PG8_BAR; PG8_SCHED;
.LBB0_319:
	s_add_u32 vcc_lo, s10, 0x100
	s_addc_u32 vcc_hi, s11, 0
	s_add_i32 s39, 0, 0x10000
	s_cmp_eq_u32 s29, 40
	s_cselect_b32 s75, s21, vcc_hi
	s_cselect_b32 s74, s20, vcc_lo
	s_cselect_b32 s73, s1, s93
	s_cselect_b32 s72, s0, s31
	s_add_i32 s30, 0, 0x14000
	s_add_i32 m0, s46, 0xc000
	global_load_lds_dwordx4 v162, s[10:11]
	s_add_i32 m0, s46, 0xe000
	s_nop 0
	global_load_lds_dwordx4 v160, s[10:11]
	v_add_u32_e32 v142, s39, v174
	v_add_u32_e32 v168, s30, v174
	ds_read_b128 v[130:133], v142
	ds_read_b128 v[134:137], v142 offset:1024
	ds_read_b128 v[138:141], v142 offset:2048
	ds_read_b128 v[142:145], v142 offset:3072
	ds_read_b128 v[146:149], v168
	ds_read_b128 v[150:153], v168 offset:1024
	ds_read_b128 v[164:167], v168 offset:2048
	ds_read_b128 v[168:171], v168 offset:3072
	ds_read_b128 v[192:195], v190
	ds_read_b128 v[204:207], v190 offset:1024
	ds_read_b128 v[208:211], v190 offset:2048
	ds_read_b128 v[212:215], v190 offset:3072
	ds_read_b128 v[216:219], v190 offset:4096
	ds_read_b128 v[220:223], v190 offset:5120
	ds_read_b128 v[224:227], v190 offset:6144
	ds_read_b128 v[242:245], v190 offset:7168
	s_waitcnt vmcnt(8)
	s_waitcnt lgkmcnt(0)
	s_setprio 1
	s_barrier
	v_mfma_f32_16x16x32_bf16 v[126:129], v[130:133], v[192:195], v[126:129]
	v_mfma_f32_16x16x32_bf16 v[122:125], v[138:141], v[192:195], v[122:125]
	v_mfma_f32_16x16x32_bf16 v[110:113], v[130:133], v[208:211], v[110:113]
	v_mfma_f32_16x16x32_bf16 v[106:109], v[138:141], v[208:211], v[106:109]
	v_mfma_f32_16x16x32_bf16 v[94:97], v[130:133], v[216:219], v[94:97]
	v_mfma_f32_16x16x32_bf16 v[90:93], v[138:141], v[216:219], v[90:93]
	v_mfma_f32_16x16x32_bf16 v[78:81], v[130:133], v[224:227], v[78:81]
	v_mfma_f32_16x16x32_bf16 v[74:77], v[138:141], v[224:227], v[74:77]
	v_mfma_f32_16x16x32_bf16 v[126:129], v[134:137], v[204:207], v[126:129]
	v_mfma_f32_16x16x32_bf16 v[122:125], v[142:145], v[204:207], v[122:125]
	v_mfma_f32_16x16x32_bf16 v[110:113], v[134:137], v[212:215], v[110:113]
	v_mfma_f32_16x16x32_bf16 v[106:109], v[142:145], v[212:215], v[106:109]
	v_mfma_f32_16x16x32_bf16 v[94:97], v[134:137], v[220:223], v[94:97]
	v_mfma_f32_16x16x32_bf16 v[90:93], v[142:145], v[220:223], v[90:93]
	v_mfma_f32_16x16x32_bf16 v[78:81], v[134:137], v[242:245], v[78:81]
	v_mfma_f32_16x16x32_bf16 v[74:77], v[142:145], v[242:245], v[74:77]
	s_setprio 0
	s_setprio 1
	v_mfma_f32_16x16x32_bf16 v[118:121], v[146:149], v[192:195], v[118:121]
	v_mfma_f32_16x16x32_bf16 v[114:117], v[164:167], v[192:195], v[114:117]
	v_mfma_f32_16x16x32_bf16 v[102:105], v[146:149], v[208:211], v[102:105]
	v_mfma_f32_16x16x32_bf16 v[98:101], v[164:167], v[208:211], v[98:101]
	v_mfma_f32_16x16x32_bf16 v[86:89], v[146:149], v[216:219], v[86:89]
	v_mfma_f32_16x16x32_bf16 v[82:85], v[164:167], v[216:219], v[82:85]
	v_mfma_f32_16x16x32_bf16 v[70:73], v[146:149], v[224:227], v[70:73]
	v_mfma_f32_16x16x32_bf16 v[66:69], v[164:167], v[224:227], v[66:69]
	v_mfma_f32_16x16x32_bf16 v[118:121], v[150:153], v[204:207], v[118:121]
	v_mfma_f32_16x16x32_bf16 v[114:117], v[168:171], v[204:207], v[114:117]
	v_mfma_f32_16x16x32_bf16 v[102:105], v[150:153], v[212:215], v[102:105]
	v_mfma_f32_16x16x32_bf16 v[98:101], v[168:171], v[212:215], v[98:101]
	v_mfma_f32_16x16x32_bf16 v[86:89], v[150:153], v[220:223], v[86:89]
	v_mfma_f32_16x16x32_bf16 v[82:85], v[168:171], v[220:223], v[82:85]
	v_mfma_f32_16x16x32_bf16 v[70:73], v[150:153], v[242:245], v[70:73]
	v_mfma_f32_16x16x32_bf16 v[66:69], v[168:171], v[242:245], v[66:69]
	s_barrier
	s_setprio 0
	s_add_i32 s10, s39, s43
	s_mov_b32 m0, s10
	global_load_lds_dwordx4 v0, s[72:73]
	s_add_i32 m0, s10, 0x2000
	s_add_u32 s10, s72, 0xb0000
	s_addc_u32 s11, s73, 0
	s_add_i32 s30, s30, s43
	global_load_lds_dwordx4 v158, s[72:73]
	s_mov_b32 m0, s30
	s_nop 0
	global_load_lds_dwordx4 v0, s[10:11]
	s_add_i32 m0, s30, 0x2000
	s_nop 0
	global_load_lds_dwordx4 v158, s[10:11]
	s_mov_b32 m0, s46
	s_nop 0
	global_load_lds_dwordx4 v154, s[74:75]
	s_mov_b32 m0, s47
	s_nop 0
	global_load_lds_dwordx4 v156, s[74:75]
	ds_read_b128 v[192:195], v190 offset:16384
	ds_read_b128 v[204:207], v190 offset:17408
	ds_read_b128 v[208:211], v190 offset:18432
	ds_read_b128 v[212:215], v190 offset:19456
	ds_read_b128 v[216:219], v190 offset:20480
	ds_read_b128 v[220:223], v190 offset:21504
	ds_read_b128 v[224:227], v190 offset:22528
	ds_read_b128 v[242:245], v190 offset:23552
	s_waitcnt vmcnt(8)
	s_waitcnt lgkmcnt(0)
	s_setprio 1
	s_barrier
	v_mfma_f32_16x16x32_bf16 v[62:65], v[130:133], v[192:195], v[62:65]
	v_mfma_f32_16x16x32_bf16 v[58:61], v[138:141], v[192:195], v[58:61]
	v_mfma_f32_16x16x32_bf16 v[46:49], v[130:133], v[208:211], v[46:49]
	v_mfma_f32_16x16x32_bf16 v[42:45], v[138:141], v[208:211], v[42:45]
	v_mfma_f32_16x16x32_bf16 v[30:33], v[130:133], v[216:219], v[30:33]
	v_mfma_f32_16x16x32_bf16 v[26:29], v[138:141], v[216:219], v[26:29]
	v_mfma_f32_16x16x32_bf16 v[14:17], v[130:133], v[224:227], v[14:17]
	v_mfma_f32_16x16x32_bf16 v[10:13], v[138:141], v[224:227], v[10:13]
	v_mfma_f32_16x16x32_bf16 v[62:65], v[134:137], v[204:207], v[62:65]
	v_mfma_f32_16x16x32_bf16 v[58:61], v[142:145], v[204:207], v[58:61]
	v_mfma_f32_16x16x32_bf16 v[46:49], v[134:137], v[212:215], v[46:49]
	v_mfma_f32_16x16x32_bf16 v[42:45], v[142:145], v[212:215], v[42:45]
	v_mfma_f32_16x16x32_bf16 v[30:33], v[134:137], v[220:223], v[30:33]
	v_mfma_f32_16x16x32_bf16 v[26:29], v[142:145], v[220:223], v[26:29]
	v_mfma_f32_16x16x32_bf16 v[14:17], v[134:137], v[242:245], v[14:17]
	v_mfma_f32_16x16x32_bf16 v[10:13], v[142:145], v[242:245], v[10:13]
	s_setprio 0
	s_setprio 1
	v_mfma_f32_16x16x32_bf16 v[54:57], v[146:149], v[192:195], v[54:57]
	v_mfma_f32_16x16x32_bf16 v[50:53], v[164:167], v[192:195], v[50:53]
	v_mfma_f32_16x16x32_bf16 v[38:41], v[146:149], v[208:211], v[38:41]
	v_mfma_f32_16x16x32_bf16 v[34:37], v[164:167], v[208:211], v[34:37]
	v_mfma_f32_16x16x32_bf16 v[22:25], v[146:149], v[216:219], v[22:25]
	v_mfma_f32_16x16x32_bf16 v[18:21], v[164:167], v[216:219], v[18:21]
	v_mfma_f32_16x16x32_bf16 v[6:9], v[146:149], v[224:227], v[6:9]
	v_mfma_f32_16x16x32_bf16 v[2:5], v[164:167], v[224:227], v[2:5]
	v_mfma_f32_16x16x32_bf16 v[54:57], v[150:153], v[204:207], v[54:57]
	v_mfma_f32_16x16x32_bf16 v[50:53], v[168:171], v[204:207], v[50:53]
	v_mfma_f32_16x16x32_bf16 v[38:41], v[150:153], v[212:215], v[38:41]
	v_mfma_f32_16x16x32_bf16 v[34:37], v[168:171], v[212:215], v[34:37]
	v_mfma_f32_16x16x32_bf16 v[22:25], v[150:153], v[220:223], v[22:25]
	v_mfma_f32_16x16x32_bf16 v[18:21], v[168:171], v[220:223], v[18:21]
	v_mfma_f32_16x16x32_bf16 v[6:9], v[150:153], v[242:245], v[6:9]
	v_mfma_f32_16x16x32_bf16 v[2:5], v[168:171], v[242:245], v[2:5]
	s_barrier
; #define PG8_STAGE(bufoff, gbase, voff) do { _Pragma("unroll") for (int _i = 0; _i < 2; ++_i) \
;         __builtin_amdgcn_global_load_lds((const gunsigned*)((const gchar*)(gbase) + (voff)[_i]), (LAS unsigned*)(lds + (bufoff) + ldsw + _i * 8192), 16, 0, 0); } while (0)
; #define PG8_LDA(dst, b, h) do { _Pragma("unroll") for (int m = 0; m < 4; ++m) _Pragma("unroll") for (int k = 0; k < 2; ++k) dst[m][k] = *(const LAS bf16x8*)(lds + PG8_SA(b, h) + aoff + m * 2048 + k * 1024); } while (0)
; #define PG8_LDB(dst, b, h) do { _Pragma("unroll") for (int n = 0; n < 2; ++n) _Pragma("unroll") for (int k = 0; k < 2; ++k) dst[n][k] = *(const LAS bf16x8*)(lds + PG8_SB(b, h) + boff + n * 2048 + k * 1024); } while (0)
; #define PG8_MMA(ai, bj, At, Bt) do { __builtin_amdgcn_s_setprio(1); _Pragma("unroll") for (int m = 0; m < 4; ++m) _Pragma("unroll") for (int n = 0; n < 2; ++n) _Pragma("unroll") for (int k = 0; k < 2; ++k) \
;         acc[ai][bj][m][n] = __builtin_amdgcn_mfma_f32_16x16x32_bf16(Bt[n][k], At[m][k], acc[ai][bj][m][n], 0, 0, 0); __builtin_amdgcn_s_setprio(0); } while (0)
; #define PG8_WAIT_V(n) asm volatile("s_waitcnt vmcnt(" #n ")" ::: "memory")
; #define PG8_WAIT_L(n) asm volatile("s_waitcnt lgkmcnt(" #n ")" ::: "memory")
; #define PG8_BAR __builtin_amdgcn_s_barrier()
; #define PG8_SCHED __builtin_amdgcn_sched_barrier(0)
; template <class Epi, class Sched>
; __device__ __forceinline__ void gemm_phase(LAS unsigned char* lds, const int tid, const Gemm g, const Sched& S, const Epi& E) {
;     ...
;             PG8_LDB(B0, 1, 0); PG8_LDB(B1, 1, 1); PG8_SCHED; PG8_LDA(At, 1, 0); PG8_STAGE(PG8_SA(0, 1), a2 + hstep, voffA);
;             PG8_WAIT_V(8); PG8_WAIT_L(0); PG8_BAR; PG8_MMA(0, 0, At, B0); PG8_MMA(0, 1, At, B1); PG8_BAR; PG8_SCHED;
;             PG8_LDA(At, 1, 1); PG8_STAGE(PG8_SB(1, 0), b3, voffB); PG8_STAGE(PG8_SB(1, 1), b3 + hstep, voffB); PG8_STAGE(PG8_SA(1, 0), a3, voffA);
;             PG8_WAIT_V(8); PG8_WAIT_L(0); PG8_BAR; PG8_MMA(1, 0, At, B0); PG8_MMA(1, 1, At, B1); PG8_BAR; PG8_SCHED;
;         }
;         if (wr == 0) PG8_BAR;
	s_setprio 0
	s_add_i32 s30, 0, 0x18000
	s_add_i32 s39, 0, 0x1c000
	s_add_u32 s10, s74, 0xb0000
	s_addc_u32 s11, s75, 0
	s_mov_b32 m0, s48
	global_load_lds_dwordx4 v154, s[10:11]
	s_mov_b32 m0, s49
	s_nop 0
	global_load_lds_dwordx4 v156, s[10:11]
	v_add_u32_e32 v142, s30, v174
	v_add_u32_e32 v168, s39, v174
	ds_read_b128 v[130:133], v142
	ds_read_b128 v[134:137], v142 offset:1024
	ds_read_b128 v[138:141], v142 offset:2048
	ds_read_b128 v[142:145], v142 offset:3072
	ds_read_b128 v[146:149], v168
	ds_read_b128 v[150:153], v168 offset:1024
	ds_read_b128 v[164:167], v168 offset:2048
	ds_read_b128 v[168:171], v168 offset:3072
	ds_read_b128 v[192:195], v190 offset:32768
	ds_read_b128 v[204:207], v190 offset:33792
	ds_read_b128 v[208:211], v190 offset:34816
	ds_read_b128 v[212:215], v190 offset:35840
	ds_read_b128 v[216:219], v190 offset:36864
	ds_read_b128 v[220:223], v190 offset:37888
	ds_read_b128 v[224:227], v190 offset:38912
	ds_read_b128 v[242:245], v190 offset:39936
	s_waitcnt vmcnt(8)
	s_waitcnt lgkmcnt(0)
	s_setprio 1
	s_barrier
	v_mfma_f32_16x16x32_bf16 v[126:129], v[130:133], v[192:195], v[126:129]
	v_mfma_f32_16x16x32_bf16 v[122:125], v[138:141], v[192:195], v[122:125]
	v_mfma_f32_16x16x32_bf16 v[110:113], v[130:133], v[208:211], v[110:113]
	v_mfma_f32_16x16x32_bf16 v[106:109], v[138:141], v[208:211], v[106:109]
	v_mfma_f32_16x16x32_bf16 v[94:97], v[130:133], v[216:219], v[94:97]
	v_mfma_f32_16x16x32_bf16 v[90:93], v[138:141], v[216:219], v[90:93]
	v_mfma_f32_16x16x32_bf16 v[78:81], v[130:133], v[224:227], v[78:81]
	v_mfma_f32_16x16x32_bf16 v[74:77], v[138:141], v[224:227], v[74:77]
	v_mfma_f32_16x16x32_bf16 v[126:129], v[134:137], v[204:207], v[126:129]
	v_mfma_f32_16x16x32_bf16 v[122:125], v[142:145], v[204:207], v[122:125]
	v_mfma_f32_16x16x32_bf16 v[110:113], v[134:137], v[212:215], v[110:113]
	v_mfma_f32_16x16x32_bf16 v[106:109], v[142:145], v[212:215], v[106:109]
	v_mfma_f32_16x16x32_bf16 v[94:97], v[134:137], v[220:223], v[94:97]
	v_mfma_f32_16x16x32_bf16 v[90:93], v[142:145], v[220:223], v[90:93]
	v_mfma_f32_16x16x32_bf16 v[78:81], v[134:137], v[242:245], v[78:81]
	v_mfma_f32_16x16x32_bf16 v[74:77], v[142:145], v[242:245], v[74:77]
	s_setprio 0
	s_setprio 1
	v_mfma_f32_16x16x32_bf16 v[118:121], v[146:149], v[192:195], v[118:121]
	v_mfma_f32_16x16x32_bf16 v[114:117], v[164:167], v[192:195], v[114:117]
	v_mfma_f32_16x16x32_bf16 v[102:105], v[146:149], v[208:211], v[102:105]
	v_mfma_f32_16x16x32_bf16 v[98:101], v[164:167], v[208:211], v[98:101]
	v_mfma_f32_16x16x32_bf16 v[86:89], v[146:149], v[216:219], v[86:89]
	v_mfma_f32_16x16x32_bf16 v[82:85], v[164:167], v[216:219], v[82:85]
	v_mfma_f32_16x16x32_bf16 v[70:73], v[146:149], v[224:227], v[70:73]
	v_mfma_f32_16x16x32_bf16 v[66:69], v[164:167], v[224:227], v[66:69]
	v_mfma_f32_16x16x32_bf16 v[118:121], v[150:153], v[204:207], v[118:121]
	v_mfma_f32_16x16x32_bf16 v[114:117], v[168:171], v[204:207], v[114:117]
	v_mfma_f32_16x16x32_bf16 v[102:105], v[150:153], v[212:215], v[102:105]
	v_mfma_f32_16x16x32_bf16 v[98:101], v[168:171], v[212:215], v[98:101]
	v_mfma_f32_16x16x32_bf16 v[86:89], v[150:153], v[220:223], v[86:89]
	v_mfma_f32_16x16x32_bf16 v[82:85], v[168:171], v[220:223], v[82:85]
	v_mfma_f32_16x16x32_bf16 v[70:73], v[150:153], v[242:245], v[70:73]
	v_mfma_f32_16x16x32_bf16 v[66:69], v[168:171], v[242:245], v[66:69]
	s_barrier
	s_setprio 0
	s_add_i32 s10, s30, s43
	s_mov_b32 m0, s10
	ds_read_b128 v[192:195], v190 offset:49152
	global_load_lds_dwordx4 v201, s[72:73]
	s_add_i32 m0, s10, 0x2000
	s_add_u32 s10, s72, 0xb0080
	s_addc_u32 s11, s73, 0
	s_add_i32 s30, s39, s43
	global_load_lds_dwordx4 v247, s[72:73]
	s_mov_b32 m0, s30
	s_nop 0
	global_load_lds_dwordx4 v0, s[10:11]
	s_add_i32 m0, s30, 0x2000
	s_nop 0
	global_load_lds_dwordx4 v158, s[10:11]
	s_mov_b32 m0, s53
	s_nop 0
	global_load_lds_dwordx4 v249, s[74:75]
	s_mov_b32 m0, s54
	s_nop 0
	global_load_lds_dwordx4 v251, s[74:75]
	ds_read_b128 v[204:207], v190 offset:50176
	ds_read_b128 v[208:211], v190 offset:51200
	ds_read_b128 v[212:215], v190 offset:52224
	ds_read_b128 v[216:219], v190 offset:53248
	ds_read_b128 v[220:223], v190 offset:54272
	ds_read_b128 v[224:227], v190 offset:55296
	ds_read_b128 v[242:245], v190 offset:56320
	s_waitcnt vmcnt(8)
	s_waitcnt lgkmcnt(0)
	s_setprio 1
	s_barrier
	v_mfma_f32_16x16x32_bf16 v[62:65], v[130:133], v[192:195], v[62:65]
	v_mfma_f32_16x16x32_bf16 v[58:61], v[138:141], v[192:195], v[58:61]
	v_mfma_f32_16x16x32_bf16 v[46:49], v[130:133], v[208:211], v[46:49]
	v_mfma_f32_16x16x32_bf16 v[42:45], v[138:141], v[208:211], v[42:45]
	v_mfma_f32_16x16x32_bf16 v[30:33], v[130:133], v[216:219], v[30:33]
	v_mfma_f32_16x16x32_bf16 v[26:29], v[138:141], v[216:219], v[26:29]
	v_mfma_f32_16x16x32_bf16 v[14:17], v[130:133], v[224:227], v[14:17]
	v_mfma_f32_16x16x32_bf16 v[10:13], v[138:141], v[224:227], v[10:13]
	v_mfma_f32_16x16x32_bf16 v[62:65], v[134:137], v[204:207], v[62:65]
	v_mfma_f32_16x16x32_bf16 v[58:61], v[142:145], v[204:207], v[58:61]
	v_mfma_f32_16x16x32_bf16 v[46:49], v[134:137], v[212:215], v[46:49]
	v_mfma_f32_16x16x32_bf16 v[42:45], v[142:145], v[212:215], v[42:45]
	v_mfma_f32_16x16x32_bf16 v[30:33], v[134:137], v[220:223], v[30:33]
	v_mfma_f32_16x16x32_bf16 v[26:29], v[142:145], v[220:223], v[26:29]
	v_mfma_f32_16x16x32_bf16 v[14:17], v[134:137], v[242:245], v[14:17]
	v_mfma_f32_16x16x32_bf16 v[10:13], v[142:145], v[242:245], v[10:13]
	s_setprio 0
	s_setprio 1
	v_mfma_f32_16x16x32_bf16 v[54:57], v[146:149], v[192:195], v[54:57]
	v_mfma_f32_16x16x32_bf16 v[50:53], v[164:167], v[192:195], v[50:53]
	v_mfma_f32_16x16x32_bf16 v[38:41], v[146:149], v[208:211], v[38:41]
	v_mfma_f32_16x16x32_bf16 v[34:37], v[164:167], v[208:211], v[34:37]
	v_mfma_f32_16x16x32_bf16 v[22:25], v[146:149], v[216:219], v[22:25]
	v_mfma_f32_16x16x32_bf16 v[18:21], v[164:167], v[216:219], v[18:21]
	v_mfma_f32_16x16x32_bf16 v[6:9], v[146:149], v[224:227], v[6:9]
	v_mfma_f32_16x16x32_bf16 v[2:5], v[164:167], v[224:227], v[2:5]
	v_mfma_f32_16x16x32_bf16 v[54:57], v[150:153], v[204:207], v[54:57]
	v_mfma_f32_16x16x32_bf16 v[50:53], v[168:171], v[204:207], v[50:53]
	v_mfma_f32_16x16x32_bf16 v[38:41], v[150:153], v[212:215], v[38:41]
	v_mfma_f32_16x16x32_bf16 v[34:37], v[168:171], v[212:215], v[34:37]
	v_mfma_f32_16x16x32_bf16 v[22:25], v[150:153], v[220:223], v[22:25]
	v_mfma_f32_16x16x32_bf16 v[18:21], v[168:171], v[220:223], v[18:21]
	v_mfma_f32_16x16x32_bf16 v[6:9], v[150:153], v[242:245], v[6:9]
	v_mfma_f32_16x16x32_bf16 v[2:5], v[168:171], v[242:245], v[2:5]
	s_barrier
	s_setprio 0
	s_add_i32 s29, s29, 2
	s_add_u32 s31, s31, 0x100
	s_addc_u32 s93, s93, 0
	s_cmp_gt_u32 s29, 41
	s_mov_b64 s[10:11], vcc
	s_cbranch_scc0 .LBB0_319
	s_and_b64 vcc, exec, s[16:17]
	s_cbranch_vccz .LBB0_322
	s_barrier

; #define PG8_STAGE(bufoff, gbase, voff) do { _Pragma("unroll") for (int _i = 0; _i < 2; ++_i) \
;         __builtin_amdgcn_global_load_lds((const gunsigned*)((const gchar*)(gbase) + (voff)[_i]), (LAS unsigned*)(lds + (bufoff) + ldsw + _i * 8192), 16, 0, 0); } while (0)
; #define PG8_LDA(dst, b, h) do { _Pragma("unroll") for (int m = 0; m < 4; ++m) _Pragma("unroll") for (int k = 0; k < 2; ++k) dst[m][k] = *(const LAS bf16x8*)(lds + PG8_SA(b, h) + aoff + m * 2048 + k * 1024); } while (0)
; #define PG8_LDB(dst, b, h) do { _Pragma("unroll") for (int n = 0; n < 2; ++n) _Pragma("unroll") for (int k = 0; k < 2; ++k) dst[n][k] = *(const LAS bf16x8*)(lds + PG8_SB(b, h) + boff + n * 2048 + k * 1024); } while (0)
; #define PG8_MMA(ai, bj, At, Bt) do { __builtin_amdgcn_s_setprio(1); _Pragma("unroll") for (int m = 0; m < 4; ++m) _Pragma("unroll") for (int n = 0; n < 2; ++n) _Pragma("unroll") for (int k = 0; k < 2; ++k) \
;         acc[ai][bj][m][n] = __builtin_amdgcn_mfma_f32_16x16x32_bf16(Bt[n][k], At[m][k], acc[ai][bj][m][n], 0, 0, 0); __builtin_amdgcn_s_setprio(0); } while (0)
; #define PG8_WAIT_V(n) asm volatile("s_waitcnt vmcnt(" #n ")" ::: "memory")
; #define PG8_WAIT_L(n) asm volatile("s_waitcnt lgkmcnt(" #n ")" ::: "memory")
; #define PG8_BAR __builtin_amdgcn_s_barrier()
; #define PG8_SCHED __builtin_amdgcn_sched_barrier(0)
; template <class Epi, class Sched>
; __device__ __forceinline__ void gemm_phase(LAS unsigned char* lds, const int tid, const Gemm g, const Sched& S, const Epi& E) {
;     ...
;             const gchar* a1 = cA + (size_t)(t + 1) * kstep;
;             const gchar* a2 = last ? nA : cA + (size_t)(t + 2) * kstep; const gchar* b2 = last ? nB : cB + (size_t)(t + 2) * kstep;
;             const gchar* a3 = a2 + kstep; const gchar* b3 = b2 + kstep;
;             PG8_LDB(B0, 0, 0); PG8_LDB(B1, 0, 1); PG8_SCHED; PG8_LDA(At, 0, 0); PG8_STAGE(PG8_SA(1, 1), a1 + hstep, voffA);
;             PG8_WAIT_V(8); PG8_WAIT_L(0); PG8_BAR; PG8_MMA(0, 0, At, B0); PG8_MMA(0, 1, At, B1); PG8_BAR; PG8_SCHED;
;             PG8_LDA(At, 0, 1); PG8_STAGE(PG8_SB(0, 0), b2, voffB); PG8_STAGE(PG8_SB(0, 1), b2 + hstep, voffB); PG8_STAGE(PG8_SA(0, 0), a2, voffA);
;             PG8_WAIT_V(8); PG8_WAIT_L(0); PG8_BAR; PG8_MMA(1, 0, At, B0); PG8_MMA(1, 1, At, B1); PG8_BAR; PG8_SCHED;
.LBB0_369:
	s_add_u32 s20, s16, 0xfffc0080
	s_addc_u32 s21, s17, -1
	s_add_i32 s29, 0, 0x10000
	s_cmp_eq_u32 s31, 12
	s_cselect_b32 s57, s11, s21
	s_cselect_b32 s56, s12, s20
	s_cselect_b32 s21, s9, s24
	s_cselect_b32 s20, s15, s23
	s_add_i32 s30, 0, 0x14000
	s_add_i32 m0, s73, 0xc000
	global_load_lds_dwordx4 v138, s[16:17]
	s_add_i32 m0, s73, 0xe000
	s_nop 0
	global_load_lds_dwordx4 v136, s[16:17]
	v_add_u32_e32 v140, s29, v145
	ds_read_b128 v[146:149], v140
	ds_read_b128 v[156:159], v140 offset:1024
	ds_read_b128 v[160:163], v140 offset:2048
	ds_read_b128 v[164:167], v140 offset:3072
	v_add_u32_e32 v140, s30, v145
	ds_read_b128 v[168:171], v140
	ds_read_b128 v[172:175], v140 offset:1024
	ds_read_b128 v[176:179], v140 offset:2048
	ds_read_b128 v[180:183], v140 offset:3072
	ds_read_b128 v[184:187], v155
	ds_read_b128 v[188:191], v155 offset:1024
	ds_read_b128 v[192:195], v155 offset:2048
	ds_read_b128 v[204:207], v155 offset:3072
	ds_read_b128 v[208:211], v155 offset:4096
	ds_read_b128 v[212:215], v155 offset:5120
	ds_read_b128 v[216:219], v155 offset:6144
	ds_read_b128 v[220:223], v155 offset:7168
	s_waitcnt vmcnt(8)
	s_waitcnt lgkmcnt(0)
	s_setprio 1
	s_barrier
	v_mfma_f32_16x16x32_bf16 v[126:129], v[146:149], v[184:187], v[126:129]
	v_mfma_f32_16x16x32_bf16 v[118:121], v[160:163], v[184:187], v[118:121]
	v_mfma_f32_16x16x32_bf16 v[110:113], v[146:149], v[192:195], v[110:113]
	v_mfma_f32_16x16x32_bf16 v[102:105], v[160:163], v[192:195], v[102:105]
	v_mfma_f32_16x16x32_bf16 v[94:97], v[146:149], v[208:211], v[94:97]
	v_mfma_f32_16x16x32_bf16 v[86:89], v[160:163], v[208:211], v[86:89]
	v_mfma_f32_16x16x32_bf16 v[78:81], v[146:149], v[216:219], v[78:81]
	v_mfma_f32_16x16x32_bf16 v[70:73], v[160:163], v[216:219], v[70:73]
	v_mfma_f32_16x16x32_bf16 v[126:129], v[156:159], v[188:191], v[126:129]
	v_mfma_f32_16x16x32_bf16 v[118:121], v[164:167], v[188:191], v[118:121]
	v_mfma_f32_16x16x32_bf16 v[110:113], v[156:159], v[204:207], v[110:113]
	v_mfma_f32_16x16x32_bf16 v[102:105], v[164:167], v[204:207], v[102:105]
	v_mfma_f32_16x16x32_bf16 v[94:97], v[156:159], v[212:215], v[94:97]
	v_mfma_f32_16x16x32_bf16 v[86:89], v[164:167], v[212:215], v[86:89]
	v_mfma_f32_16x16x32_bf16 v[78:81], v[156:159], v[220:223], v[78:81]
	v_mfma_f32_16x16x32_bf16 v[70:73], v[164:167], v[220:223], v[70:73]
	s_setprio 0
	s_setprio 1
	v_mfma_f32_16x16x32_bf16 v[122:125], v[168:171], v[184:187], v[122:125]
	v_mfma_f32_16x16x32_bf16 v[114:117], v[176:179], v[184:187], v[114:117]
	v_mfma_f32_16x16x32_bf16 v[106:109], v[168:171], v[192:195], v[106:109]
	v_mfma_f32_16x16x32_bf16 v[98:101], v[176:179], v[192:195], v[98:101]
	v_mfma_f32_16x16x32_bf16 v[90:93], v[168:171], v[208:211], v[90:93]
	v_mfma_f32_16x16x32_bf16 v[82:85], v[176:179], v[208:211], v[82:85]
	v_mfma_f32_16x16x32_bf16 v[74:77], v[168:171], v[216:219], v[74:77]
	v_mfma_f32_16x16x32_bf16 v[66:69], v[176:179], v[216:219], v[66:69]
	v_mfma_f32_16x16x32_bf16 v[122:125], v[172:175], v[188:191], v[122:125]
	v_mfma_f32_16x16x32_bf16 v[114:117], v[180:183], v[188:191], v[114:117]
	v_mfma_f32_16x16x32_bf16 v[106:109], v[172:175], v[204:207], v[106:109]
	v_mfma_f32_16x16x32_bf16 v[98:101], v[180:183], v[204:207], v[98:101]
	v_mfma_f32_16x16x32_bf16 v[90:93], v[172:175], v[212:215], v[90:93]
	v_mfma_f32_16x16x32_bf16 v[82:85], v[180:183], v[212:215], v[82:85]
	v_mfma_f32_16x16x32_bf16 v[74:77], v[172:175], v[220:223], v[74:77]
	v_mfma_f32_16x16x32_bf16 v[66:69], v[180:183], v[220:223], v[66:69]
	s_barrier
	s_setprio 0
	s_add_i32 s29, s29, s43
	s_mov_b32 m0, s29
	global_load_lds_dwordx4 v0, s[20:21]
	s_add_i32 m0, s29, 0x2000
	s_add_u32 s46, s20, 0x40000
	s_addc_u32 s47, s21, 0
	s_add_i32 s29, s30, s43
	global_load_lds_dwordx4 v130, s[20:21]
	s_mov_b32 m0, s29
	s_nop 0
	global_load_lds_dwordx4 v0, s[46:47]
	s_add_i32 m0, s29, 0x2000
	s_nop 0
	global_load_lds_dwordx4 v130, s[46:47]
	s_mov_b32 m0, s73
	s_nop 0
	global_load_lds_dwordx4 v134, s[56:57]
	s_mov_b32 m0, s74
	s_nop 0
	global_load_lds_dwordx4 v132, s[56:57]
	ds_read_b128 v[184:187], v155 offset:16384
	ds_read_b128 v[188:191], v155 offset:17408
	ds_read_b128 v[192:195], v155 offset:18432
	ds_read_b128 v[204:207], v155 offset:19456
	ds_read_b128 v[208:211], v155 offset:20480
	ds_read_b128 v[212:215], v155 offset:21504
	ds_read_b128 v[216:219], v155 offset:22528
	ds_read_b128 v[220:223], v155 offset:23552
	s_waitcnt vmcnt(8)
	s_waitcnt lgkmcnt(0)
	s_setprio 1
	s_barrier
	v_mfma_f32_16x16x32_bf16 v[62:65], v[146:149], v[184:187], v[62:65]
	v_mfma_f32_16x16x32_bf16 v[54:57], v[160:163], v[184:187], v[54:57]
	v_mfma_f32_16x16x32_bf16 v[46:49], v[146:149], v[192:195], v[46:49]
	v_mfma_f32_16x16x32_bf16 v[38:41], v[160:163], v[192:195], v[38:41]
	v_mfma_f32_16x16x32_bf16 v[30:33], v[146:149], v[208:211], v[30:33]
	v_mfma_f32_16x16x32_bf16 v[22:25], v[160:163], v[208:211], v[22:25]
	v_mfma_f32_16x16x32_bf16 v[14:17], v[146:149], v[216:219], v[14:17]
	v_mfma_f32_16x16x32_bf16 v[6:9], v[160:163], v[216:219], v[6:9]
	v_mfma_f32_16x16x32_bf16 v[62:65], v[156:159], v[188:191], v[62:65]
	v_mfma_f32_16x16x32_bf16 v[54:57], v[164:167], v[188:191], v[54:57]
	v_mfma_f32_16x16x32_bf16 v[46:49], v[156:159], v[204:207], v[46:49]
	v_mfma_f32_16x16x32_bf16 v[38:41], v[164:167], v[204:207], v[38:41]
	v_mfma_f32_16x16x32_bf16 v[30:33], v[156:159], v[212:215], v[30:33]
	v_mfma_f32_16x16x32_bf16 v[22:25], v[164:167], v[212:215], v[22:25]
	v_mfma_f32_16x16x32_bf16 v[14:17], v[156:159], v[220:223], v[14:17]
	v_mfma_f32_16x16x32_bf16 v[6:9], v[164:167], v[220:223], v[6:9]
	s_setprio 0
	s_setprio 1
	v_mfma_f32_16x16x32_bf16 v[58:61], v[168:171], v[184:187], v[58:61]
	v_mfma_f32_16x16x32_bf16 v[50:53], v[176:179], v[184:187], v[50:53]
	v_mfma_f32_16x16x32_bf16 v[42:45], v[168:171], v[192:195], v[42:45]
	v_mfma_f32_16x16x32_bf16 v[34:37], v[176:179], v[192:195], v[34:37]
	v_mfma_f32_16x16x32_bf16 v[26:29], v[168:171], v[208:211], v[26:29]
	v_mfma_f32_16x16x32_bf16 v[18:21], v[176:179], v[208:211], v[18:21]
	v_mfma_f32_16x16x32_bf16 v[10:13], v[168:171], v[216:219], v[10:13]
	v_mfma_f32_16x16x32_bf16 v[2:5], v[176:179], v[216:219], v[2:5]
	v_mfma_f32_16x16x32_bf16 v[58:61], v[172:175], v[188:191], v[58:61]
	v_mfma_f32_16x16x32_bf16 v[50:53], v[180:183], v[188:191], v[50:53]
	v_mfma_f32_16x16x32_bf16 v[42:45], v[172:175], v[204:207], v[42:45]
	v_mfma_f32_16x16x32_bf16 v[34:37], v[180:183], v[204:207], v[34:37]
	v_mfma_f32_16x16x32_bf16 v[26:29], v[172:175], v[212:215], v[26:29]
	v_mfma_f32_16x16x32_bf16 v[18:21], v[180:183], v[212:215], v[18:21]
	v_mfma_f32_16x16x32_bf16 v[10:13], v[172:175], v[220:223], v[10:13]
	v_mfma_f32_16x16x32_bf16 v[2:5], v[180:183], v[220:223], v[2:5]
	s_barrier
; #define PG8_STAGE(bufoff, gbase, voff) do { _Pragma("unroll") for (int _i = 0; _i < 2; ++_i) \
;         __builtin_amdgcn_global_load_lds((const gunsigned*)((const gchar*)(gbase) + (voff)[_i]), (LAS unsigned*)(lds + (bufoff) + ldsw + _i * 8192), 16, 0, 0); } while (0)
; #define PG8_LDA(dst, b, h) do { _Pragma("unroll") for (int m = 0; m < 4; ++m) _Pragma("unroll") for (int k = 0; k < 2; ++k) dst[m][k] = *(const LAS bf16x8*)(lds + PG8_SA(b, h) + aoff + m * 2048 + k * 1024); } while (0)
; #define PG8_LDB(dst, b, h) do { _Pragma("unroll") for (int n = 0; n < 2; ++n) _Pragma("unroll") for (int k = 0; k < 2; ++k) dst[n][k] = *(const LAS bf16x8*)(lds + PG8_SB(b, h) + boff + n * 2048 + k * 1024); } while (0)
; #define PG8_MMA(ai, bj, At, Bt) do { __builtin_amdgcn_s_setprio(1); _Pragma("unroll") for (int m = 0; m < 4; ++m) _Pragma("unroll") for (int n = 0; n < 2; ++n) _Pragma("unroll") for (int k = 0; k < 2; ++k) \
;         acc[ai][bj][m][n] = __builtin_amdgcn_mfma_f32_16x16x32_bf16(Bt[n][k], At[m][k], acc[ai][bj][m][n], 0, 0, 0); __builtin_amdgcn_s_setprio(0); } while (0)
; #define PG8_WAIT_V(n) asm volatile("s_waitcnt vmcnt(" #n ")" ::: "memory")
; #define PG8_WAIT_L(n) asm volatile("s_waitcnt lgkmcnt(" #n ")" ::: "memory")
; #define PG8_BAR __builtin_amdgcn_s_barrier()
; #define PG8_SCHED __builtin_amdgcn_sched_barrier(0)
; template <class Epi, class Sched>
; __device__ __forceinline__ void gemm_phase(LAS unsigned char* lds, const int tid, const Gemm g, const Sched& S, const Epi& E) {
;     ...
;             PG8_LDB(B0, 1, 0); PG8_LDB(B1, 1, 1); PG8_SCHED; PG8_LDA(At, 1, 0); PG8_STAGE(PG8_SA(0, 1), a2 + hstep, voffA);
;             PG8_WAIT_V(8); PG8_WAIT_L(0); PG8_BAR; PG8_MMA(0, 0, At, B0); PG8_MMA(0, 1, At, B1); PG8_BAR; PG8_SCHED;
;             PG8_LDA(At, 1, 1); PG8_STAGE(PG8_SB(1, 0), b3, voffB); PG8_STAGE(PG8_SB(1, 1), b3 + hstep, voffB); PG8_STAGE(PG8_SA(1, 0), a3, voffA);
;             PG8_WAIT_V(8); PG8_WAIT_L(0); PG8_BAR; PG8_MMA(1, 0, At, B0); PG8_MMA(1, 1, At, B1); PG8_BAR; PG8_SCHED;
;         }
;         if (wr == 0) PG8_BAR;
	s_setprio 0
	s_add_i32 s29, 0, 0x18000
	v_add_u32_e32 v142, s29, v145
	s_add_i32 s30, 0, 0x1c000
	s_add_u32 s46, s56, 0x40000
	s_addc_u32 s47, s57, 0
	s_mov_b32 m0, s75
	global_load_lds_dwordx4 v134, s[46:47]
	s_mov_b32 m0, s92
	s_nop 0
	global_load_lds_dwordx4 v132, s[46:47]
	ds_read_b128 v[146:149], v142
	ds_read_b128 v[156:159], v142 offset:1024
	ds_read_b128 v[160:163], v142 offset:2048
	ds_read_b128 v[164:167], v142 offset:3072
	v_add_u32_e32 v142, s30, v145
	ds_read_b128 v[168:171], v142
	ds_read_b128 v[172:175], v142 offset:1024
	ds_read_b128 v[176:179], v142 offset:2048
	ds_read_b128 v[180:183], v142 offset:3072
	ds_read_b128 v[184:187], v155 offset:32768
	ds_read_b128 v[188:191], v155 offset:33792
	ds_read_b128 v[192:195], v155 offset:34816
	ds_read_b128 v[204:207], v155 offset:35840
	ds_read_b128 v[208:211], v155 offset:36864
	ds_read_b128 v[212:215], v155 offset:37888
	ds_read_b128 v[216:219], v155 offset:38912
	ds_read_b128 v[220:223], v155 offset:39936
	s_waitcnt vmcnt(8)
	s_waitcnt lgkmcnt(0)
	s_setprio 1
	s_barrier
	v_mfma_f32_16x16x32_bf16 v[126:129], v[146:149], v[184:187], v[126:129]
	v_mfma_f32_16x16x32_bf16 v[118:121], v[160:163], v[184:187], v[118:121]
	v_mfma_f32_16x16x32_bf16 v[110:113], v[146:149], v[192:195], v[110:113]
	v_mfma_f32_16x16x32_bf16 v[102:105], v[160:163], v[192:195], v[102:105]
	v_mfma_f32_16x16x32_bf16 v[94:97], v[146:149], v[208:211], v[94:97]
	v_mfma_f32_16x16x32_bf16 v[86:89], v[160:163], v[208:211], v[86:89]
	v_mfma_f32_16x16x32_bf16 v[78:81], v[146:149], v[216:219], v[78:81]
	v_mfma_f32_16x16x32_bf16 v[70:73], v[160:163], v[216:219], v[70:73]
	v_mfma_f32_16x16x32_bf16 v[126:129], v[156:159], v[188:191], v[126:129]
	v_mfma_f32_16x16x32_bf16 v[118:121], v[164:167], v[188:191], v[118:121]
	v_mfma_f32_16x16x32_bf16 v[110:113], v[156:159], v[204:207], v[110:113]
	v_mfma_f32_16x16x32_bf16 v[102:105], v[164:167], v[204:207], v[102:105]
	v_mfma_f32_16x16x32_bf16 v[94:97], v[156:159], v[212:215], v[94:97]
	v_mfma_f32_16x16x32_bf16 v[86:89], v[164:167], v[212:215], v[86:89]
	v_mfma_f32_16x16x32_bf16 v[78:81], v[156:159], v[220:223], v[78:81]
	v_mfma_f32_16x16x32_bf16 v[70:73], v[164:167], v[220:223], v[70:73]
	s_setprio 0
	s_setprio 1
	v_mfma_f32_16x16x32_bf16 v[122:125], v[168:171], v[184:187], v[122:125]
	v_mfma_f32_16x16x32_bf16 v[114:117], v[176:179], v[184:187], v[114:117]
	v_mfma_f32_16x16x32_bf16 v[106:109], v[168:171], v[192:195], v[106:109]
	v_mfma_f32_16x16x32_bf16 v[98:101], v[176:179], v[192:195], v[98:101]
	v_mfma_f32_16x16x32_bf16 v[90:93], v[168:171], v[208:211], v[90:93]
	v_mfma_f32_16x16x32_bf16 v[82:85], v[176:179], v[208:211], v[82:85]
	v_mfma_f32_16x16x32_bf16 v[74:77], v[168:171], v[216:219], v[74:77]
	v_mfma_f32_16x16x32_bf16 v[66:69], v[176:179], v[216:219], v[66:69]
	v_mfma_f32_16x16x32_bf16 v[122:125], v[172:175], v[188:191], v[122:125]
	v_mfma_f32_16x16x32_bf16 v[114:117], v[180:183], v[188:191], v[114:117]
	v_mfma_f32_16x16x32_bf16 v[106:109], v[172:175], v[204:207], v[106:109]
	v_mfma_f32_16x16x32_bf16 v[98:101], v[180:183], v[204:207], v[98:101]
	v_mfma_f32_16x16x32_bf16 v[90:93], v[172:175], v[212:215], v[90:93]
	v_mfma_f32_16x16x32_bf16 v[82:85], v[180:183], v[212:215], v[82:85]
	v_mfma_f32_16x16x32_bf16 v[74:77], v[172:175], v[220:223], v[74:77]
	v_mfma_f32_16x16x32_bf16 v[66:69], v[180:183], v[220:223], v[66:69]
	s_barrier
	s_setprio 0
	s_add_i32 s29, s29, s43
	s_mov_b32 m0, s29
	ds_read_b128 v[184:187], v155 offset:49152
	global_load_lds_dwordx4 v141, s[20:21]
	s_add_i32 m0, s29, 0x2000
	s_add_i32 s29, s30, s43
	global_load_lds_dwordx4 v153, s[20:21]
	s_add_u32 s20, s20, 0x40080
	s_addc_u32 s21, s21, 0
	s_mov_b32 m0, s29
	s_nop 0
	global_load_lds_dwordx4 v0, s[20:21]
	s_add_i32 m0, s29, 0x2000
	s_nop 0
	global_load_lds_dwordx4 v130, s[20:21]
	s_mov_b32 m0, s93
	s_nop 0
	global_load_lds_dwordx4 v201, s[56:57]
	s_mov_b32 m0, s44
	s_nop 0
	global_load_lds_dwordx4 v225, s[56:57]
	ds_read_b128 v[188:191], v155 offset:50176
	ds_read_b128 v[192:195], v155 offset:51200
	ds_read_b128 v[204:207], v155 offset:52224
	ds_read_b128 v[208:211], v155 offset:53248
	ds_read_b128 v[212:215], v155 offset:54272
	ds_read_b128 v[216:219], v155 offset:55296
	ds_read_b128 v[220:223], v155 offset:56320
	s_waitcnt vmcnt(8)
	s_waitcnt lgkmcnt(0)
	s_setprio 1
	s_barrier
	v_mfma_f32_16x16x32_bf16 v[62:65], v[146:149], v[184:187], v[62:65]
	v_mfma_f32_16x16x32_bf16 v[54:57], v[160:163], v[184:187], v[54:57]
	v_mfma_f32_16x16x32_bf16 v[46:49], v[146:149], v[192:195], v[46:49]
	v_mfma_f32_16x16x32_bf16 v[38:41], v[160:163], v[192:195], v[38:41]
	v_mfma_f32_16x16x32_bf16 v[30:33], v[146:149], v[208:211], v[30:33]
	v_mfma_f32_16x16x32_bf16 v[22:25], v[160:163], v[208:211], v[22:25]
	v_mfma_f32_16x16x32_bf16 v[14:17], v[146:149], v[216:219], v[14:17]
	v_mfma_f32_16x16x32_bf16 v[6:9], v[160:163], v[216:219], v[6:9]
	v_mfma_f32_16x16x32_bf16 v[62:65], v[156:159], v[188:191], v[62:65]
	v_mfma_f32_16x16x32_bf16 v[54:57], v[164:167], v[188:191], v[54:57]
	v_mfma_f32_16x16x32_bf16 v[46:49], v[156:159], v[204:207], v[46:49]
	v_mfma_f32_16x16x32_bf16 v[38:41], v[164:167], v[204:207], v[38:41]
	v_mfma_f32_16x16x32_bf16 v[30:33], v[156:159], v[212:215], v[30:33]
	v_mfma_f32_16x16x32_bf16 v[22:25], v[164:167], v[212:215], v[22:25]
	v_mfma_f32_16x16x32_bf16 v[14:17], v[156:159], v[220:223], v[14:17]
	v_mfma_f32_16x16x32_bf16 v[6:9], v[164:167], v[220:223], v[6:9]
	s_setprio 0
	s_setprio 1
	v_mfma_f32_16x16x32_bf16 v[58:61], v[168:171], v[184:187], v[58:61]
	v_mfma_f32_16x16x32_bf16 v[50:53], v[176:179], v[184:187], v[50:53]
	v_mfma_f32_16x16x32_bf16 v[42:45], v[168:171], v[192:195], v[42:45]
	v_mfma_f32_16x16x32_bf16 v[34:37], v[176:179], v[192:195], v[34:37]
	v_mfma_f32_16x16x32_bf16 v[26:29], v[168:171], v[208:211], v[26:29]
	v_mfma_f32_16x16x32_bf16 v[18:21], v[176:179], v[208:211], v[18:21]
	v_mfma_f32_16x16x32_bf16 v[10:13], v[168:171], v[216:219], v[10:13]
	v_mfma_f32_16x16x32_bf16 v[2:5], v[176:179], v[216:219], v[2:5]
	v_mfma_f32_16x16x32_bf16 v[58:61], v[172:175], v[188:191], v[58:61]
	v_mfma_f32_16x16x32_bf16 v[50:53], v[180:183], v[188:191], v[50:53]
	v_mfma_f32_16x16x32_bf16 v[42:45], v[172:175], v[204:207], v[42:45]
	v_mfma_f32_16x16x32_bf16 v[34:37], v[180:183], v[204:207], v[34:37]
	v_mfma_f32_16x16x32_bf16 v[26:29], v[172:175], v[212:215], v[26:29]
	v_mfma_f32_16x16x32_bf16 v[18:21], v[180:183], v[212:215], v[18:21]
	v_mfma_f32_16x16x32_bf16 v[10:13], v[172:175], v[220:223], v[10:13]
	v_mfma_f32_16x16x32_bf16 v[2:5], v[180:183], v[220:223], v[2:5]
	s_barrier
	s_setprio 0
	s_add_i32 s31, s31, 2
	s_add_u32 s23, s23, 0x100
	s_addc_u32 s24, s24, 0
	s_add_u32 s16, s16, 0x100
	s_addc_u32 s17, s17, 0
	s_cmp_gt_u32 s31, 13
	s_cbranch_scc0 .LBB0_369
	s_and_b64 vcc, exec, s[6:7]
	s_cbranch_vccz .LBB0_372
	s_barrier

; #define PG8_STAGE(bufoff, gbase, voff) do { _Pragma("unroll") for (int _i = 0; _i < 2; ++_i) \
;         __builtin_amdgcn_global_load_lds((const gunsigned*)((const gchar*)(gbase) + (voff)[_i]), (LAS unsigned*)(lds + (bufoff) + ldsw + _i * 8192), 16, 0, 0); } while (0)
; #define PG8_LDA(dst, b, h) do { _Pragma("unroll") for (int m = 0; m < 4; ++m) _Pragma("unroll") for (int k = 0; k < 2; ++k) dst[m][k] = *(const LAS bf16x8*)(lds + PG8_SA(b, h) + aoff + m * 2048 + k * 1024); } while (0)
; #define PG8_LDB(dst, b, h) do { _Pragma("unroll") for (int n = 0; n < 2; ++n) _Pragma("unroll") for (int k = 0; k < 2; ++k) dst[n][k] = *(const LAS bf16x8*)(lds + PG8_SB(b, h) + boff + n * 2048 + k * 1024); } while (0)
; #define PG8_MMA(ai, bj, At, Bt) do { __builtin_amdgcn_s_setprio(1); _Pragma("unroll") for (int m = 0; m < 4; ++m) _Pragma("unroll") for (int n = 0; n < 2; ++n) _Pragma("unroll") for (int k = 0; k < 2; ++k) \
;         acc[ai][bj][m][n] = __builtin_amdgcn_mfma_f32_16x16x32_bf16(Bt[n][k], At[m][k], acc[ai][bj][m][n], 0, 0, 0); __builtin_amdgcn_s_setprio(0); } while (0)
; #define PG8_WAIT_V(n) asm volatile("s_waitcnt vmcnt(" #n ")" ::: "memory")
; #define PG8_WAIT_L(n) asm volatile("s_waitcnt lgkmcnt(" #n ")" ::: "memory")
; #define PG8_BAR __builtin_amdgcn_s_barrier()
; #define PG8_SCHED __builtin_amdgcn_sched_barrier(0)
; template <class Epi, class Sched>
; __device__ __forceinline__ void gemm_phase(LAS unsigned char* lds, const int tid, const Gemm g, const Sched& S, const Epi& E) {
;     ...
;             const gchar* a1 = cA + (size_t)(t + 1) * kstep;
;             const gchar* a2 = last ? nA : cA + (size_t)(t + 2) * kstep; const gchar* b2 = last ? nB : cB + (size_t)(t + 2) * kstep;
;             const gchar* a3 = a2 + kstep; const gchar* b3 = b2 + kstep;
;             PG8_LDB(B0, 0, 0); PG8_LDB(B1, 0, 1); PG8_SCHED; PG8_LDA(At, 0, 0); PG8_STAGE(PG8_SA(1, 1), a1 + hstep, voffA);
;             PG8_WAIT_V(8); PG8_WAIT_L(0); PG8_BAR; PG8_MMA(0, 0, At, B0); PG8_MMA(0, 1, At, B1); PG8_BAR; PG8_SCHED;
;             PG8_LDA(At, 0, 1); PG8_STAGE(PG8_SB(0, 0), b2, voffB); PG8_STAGE(PG8_SB(0, 1), b2 + hstep, voffB); PG8_STAGE(PG8_SA(0, 0), a2, voffA);
;             PG8_WAIT_V(8); PG8_WAIT_L(0); PG8_BAR; PG8_MMA(1, 0, At, B0); PG8_MMA(1, 1, At, B1); PG8_BAR; PG8_SCHED;
.LBB0_397:
	s_add_u32 s20, s92, 0xfffc0080
	s_addc_u32 s21, s93, -1
	s_add_i32 s29, 0, 0x10000
	s_cmp_eq_u32 s53, 12
	s_cselect_b32 s73, s1, s21
	s_cselect_b32 s72, s31, s20
	s_cselect_b32 s21, s17, s52
	s_cselect_b32 s20, s50, s51
	s_add_i32 s30, 0, 0x14000
	s_add_i32 m0, s43, 0xc000
	global_load_lds_dwordx4 v162, s[92:93]
	s_add_i32 m0, s43, 0xe000
	s_nop 0
	global_load_lds_dwordx4 v160, s[92:93]
	v_add_u32_e32 v142, s29, v177
	v_add_u32_e32 v168, s30, v177
	ds_read_b128 v[130:133], v142
	ds_read_b128 v[134:137], v142 offset:1024
	ds_read_b128 v[138:141], v142 offset:2048
	ds_read_b128 v[142:145], v142 offset:3072
	ds_read_b128 v[146:149], v168
	ds_read_b128 v[150:153], v168 offset:1024
	ds_read_b128 v[164:167], v168 offset:2048
	ds_read_b128 v[168:171], v168 offset:3072
	ds_read_b128 v[172:175], v181
	ds_read_b128 v[182:185], v181 offset:1024
	ds_read_b128 v[186:189], v181 offset:2048
	ds_read_b128 v[190:193], v181 offset:3072
	ds_read_b128 v[204:207], v181 offset:4096
	ds_read_b128 v[208:211], v181 offset:5120
	ds_read_b128 v[212:215], v181 offset:6144
	ds_read_b128 v[216:219], v181 offset:7168
	s_waitcnt vmcnt(8)
	s_waitcnt lgkmcnt(0)
	s_setprio 1
	s_barrier
	v_mfma_f32_16x16x32_bf16 v[126:129], v[130:133], v[172:175], v[126:129]
	v_mfma_f32_16x16x32_bf16 v[122:125], v[138:141], v[172:175], v[122:125]
	v_mfma_f32_16x16x32_bf16 v[110:113], v[130:133], v[186:189], v[110:113]
	v_mfma_f32_16x16x32_bf16 v[106:109], v[138:141], v[186:189], v[106:109]
	v_mfma_f32_16x16x32_bf16 v[94:97], v[130:133], v[204:207], v[94:97]
	v_mfma_f32_16x16x32_bf16 v[90:93], v[138:141], v[204:207], v[90:93]
	v_mfma_f32_16x16x32_bf16 v[78:81], v[130:133], v[212:215], v[78:81]
	v_mfma_f32_16x16x32_bf16 v[74:77], v[138:141], v[212:215], v[74:77]
	v_mfma_f32_16x16x32_bf16 v[126:129], v[134:137], v[182:185], v[126:129]
	v_mfma_f32_16x16x32_bf16 v[122:125], v[142:145], v[182:185], v[122:125]
	v_mfma_f32_16x16x32_bf16 v[110:113], v[134:137], v[190:193], v[110:113]
	v_mfma_f32_16x16x32_bf16 v[106:109], v[142:145], v[190:193], v[106:109]
	v_mfma_f32_16x16x32_bf16 v[94:97], v[134:137], v[208:211], v[94:97]
	v_mfma_f32_16x16x32_bf16 v[90:93], v[142:145], v[208:211], v[90:93]
	v_mfma_f32_16x16x32_bf16 v[78:81], v[134:137], v[216:219], v[78:81]
	v_mfma_f32_16x16x32_bf16 v[74:77], v[142:145], v[216:219], v[74:77]
	s_setprio 0
	s_setprio 1
	v_mfma_f32_16x16x32_bf16 v[118:121], v[146:149], v[172:175], v[118:121]
	v_mfma_f32_16x16x32_bf16 v[114:117], v[164:167], v[172:175], v[114:117]
	v_mfma_f32_16x16x32_bf16 v[102:105], v[146:149], v[186:189], v[102:105]
	v_mfma_f32_16x16x32_bf16 v[98:101], v[164:167], v[186:189], v[98:101]
	v_mfma_f32_16x16x32_bf16 v[86:89], v[146:149], v[204:207], v[86:89]
	v_mfma_f32_16x16x32_bf16 v[82:85], v[164:167], v[204:207], v[82:85]
	v_mfma_f32_16x16x32_bf16 v[70:73], v[146:149], v[212:215], v[70:73]
	v_mfma_f32_16x16x32_bf16 v[66:69], v[164:167], v[212:215], v[66:69]
	v_mfma_f32_16x16x32_bf16 v[118:121], v[150:153], v[182:185], v[118:121]
	v_mfma_f32_16x16x32_bf16 v[114:117], v[168:171], v[182:185], v[114:117]
	v_mfma_f32_16x16x32_bf16 v[102:105], v[150:153], v[190:193], v[102:105]
	v_mfma_f32_16x16x32_bf16 v[98:101], v[168:171], v[190:193], v[98:101]
	v_mfma_f32_16x16x32_bf16 v[86:89], v[150:153], v[208:211], v[86:89]
	v_mfma_f32_16x16x32_bf16 v[82:85], v[168:171], v[208:211], v[82:85]
	v_mfma_f32_16x16x32_bf16 v[70:73], v[150:153], v[216:219], v[70:73]
	v_mfma_f32_16x16x32_bf16 v[66:69], v[168:171], v[216:219], v[66:69]
	s_barrier
	s_setprio 0
	s_add_i32 s29, s29, s15
	s_mov_b32 m0, s29
	global_load_lds_dwordx4 v0, s[20:21]
	s_add_i32 m0, s29, 0x2000
	s_add_u32 s54, s20, 0x40000
	s_addc_u32 s55, s21, 0
	s_add_i32 s29, s30, s15
	global_load_lds_dwordx4 v158, s[20:21]
	s_mov_b32 m0, s29
	s_nop 0
	global_load_lds_dwordx4 v0, s[54:55]
	s_add_i32 m0, s29, 0x2000
	s_nop 0
	global_load_lds_dwordx4 v158, s[54:55]
	s_mov_b32 m0, s43
	s_nop 0
	global_load_lds_dwordx4 v154, s[72:73]
	s_mov_b32 m0, s44
	s_nop 0
	global_load_lds_dwordx4 v156, s[72:73]
	ds_read_b128 v[172:175], v181 offset:16384
	ds_read_b128 v[182:185], v181 offset:17408
	ds_read_b128 v[186:189], v181 offset:18432
	ds_read_b128 v[190:193], v181 offset:19456
	ds_read_b128 v[204:207], v181 offset:20480
	ds_read_b128 v[208:211], v181 offset:21504
	ds_read_b128 v[212:215], v181 offset:22528
	ds_read_b128 v[216:219], v181 offset:23552
	s_waitcnt vmcnt(8)
	s_waitcnt lgkmcnt(0)
	s_setprio 1
	s_barrier
	v_mfma_f32_16x16x32_bf16 v[62:65], v[130:133], v[172:175], v[62:65]
	v_mfma_f32_16x16x32_bf16 v[58:61], v[138:141], v[172:175], v[58:61]
	v_mfma_f32_16x16x32_bf16 v[46:49], v[130:133], v[186:189], v[46:49]
	v_mfma_f32_16x16x32_bf16 v[42:45], v[138:141], v[186:189], v[42:45]
	v_mfma_f32_16x16x32_bf16 v[30:33], v[130:133], v[204:207], v[30:33]
	v_mfma_f32_16x16x32_bf16 v[26:29], v[138:141], v[204:207], v[26:29]
	v_mfma_f32_16x16x32_bf16 v[14:17], v[130:133], v[212:215], v[14:17]
	v_mfma_f32_16x16x32_bf16 v[10:13], v[138:141], v[212:215], v[10:13]
	v_mfma_f32_16x16x32_bf16 v[62:65], v[134:137], v[182:185], v[62:65]
	v_mfma_f32_16x16x32_bf16 v[58:61], v[142:145], v[182:185], v[58:61]
	v_mfma_f32_16x16x32_bf16 v[46:49], v[134:137], v[190:193], v[46:49]
	v_mfma_f32_16x16x32_bf16 v[42:45], v[142:145], v[190:193], v[42:45]
	v_mfma_f32_16x16x32_bf16 v[30:33], v[134:137], v[208:211], v[30:33]
	v_mfma_f32_16x16x32_bf16 v[26:29], v[142:145], v[208:211], v[26:29]
	v_mfma_f32_16x16x32_bf16 v[14:17], v[134:137], v[216:219], v[14:17]
	v_mfma_f32_16x16x32_bf16 v[10:13], v[142:145], v[216:219], v[10:13]
	s_setprio 0
	s_setprio 1
	v_mfma_f32_16x16x32_bf16 v[54:57], v[146:149], v[172:175], v[54:57]
	v_mfma_f32_16x16x32_bf16 v[50:53], v[164:167], v[172:175], v[50:53]
	v_mfma_f32_16x16x32_bf16 v[38:41], v[146:149], v[186:189], v[38:41]
	v_mfma_f32_16x16x32_bf16 v[34:37], v[164:167], v[186:189], v[34:37]
	v_mfma_f32_16x16x32_bf16 v[22:25], v[146:149], v[204:207], v[22:25]
	v_mfma_f32_16x16x32_bf16 v[18:21], v[164:167], v[204:207], v[18:21]
	v_mfma_f32_16x16x32_bf16 v[6:9], v[146:149], v[212:215], v[6:9]
	v_mfma_f32_16x16x32_bf16 v[2:5], v[164:167], v[212:215], v[2:5]
	v_mfma_f32_16x16x32_bf16 v[54:57], v[150:153], v[182:185], v[54:57]
	v_mfma_f32_16x16x32_bf16 v[50:53], v[168:171], v[182:185], v[50:53]
	v_mfma_f32_16x16x32_bf16 v[38:41], v[150:153], v[190:193], v[38:41]
	v_mfma_f32_16x16x32_bf16 v[34:37], v[168:171], v[190:193], v[34:37]
	v_mfma_f32_16x16x32_bf16 v[22:25], v[150:153], v[208:211], v[22:25]
	v_mfma_f32_16x16x32_bf16 v[18:21], v[168:171], v[208:211], v[18:21]
	v_mfma_f32_16x16x32_bf16 v[6:9], v[150:153], v[216:219], v[6:9]
	v_mfma_f32_16x16x32_bf16 v[2:5], v[168:171], v[216:219], v[2:5]
	s_barrier
; #define PG8_STAGE(bufoff, gbase, voff) do { _Pragma("unroll") for (int _i = 0; _i < 2; ++_i) \
;         __builtin_amdgcn_global_load_lds((const gunsigned*)((const gchar*)(gbase) + (voff)[_i]), (LAS unsigned*)(lds + (bufoff) + ldsw + _i * 8192), 16, 0, 0); } while (0)
; #define PG8_LDA(dst, b, h) do { _Pragma("unroll") for (int m = 0; m < 4; ++m) _Pragma("unroll") for (int k = 0; k < 2; ++k) dst[m][k] = *(const LAS bf16x8*)(lds + PG8_SA(b, h) + aoff + m * 2048 + k * 1024); } while (0)
; #define PG8_LDB(dst, b, h) do { _Pragma("unroll") for (int n = 0; n < 2; ++n) _Pragma("unroll") for (int k = 0; k < 2; ++k) dst[n][k] = *(const LAS bf16x8*)(lds + PG8_SB(b, h) + boff + n * 2048 + k * 1024); } while (0)
; #define PG8_MMA(ai, bj, At, Bt) do { __builtin_amdgcn_s_setprio(1); _Pragma("unroll") for (int m = 0; m < 4; ++m) _Pragma("unroll") for (int n = 0; n < 2; ++n) _Pragma("unroll") for (int k = 0; k < 2; ++k) \
;         acc[ai][bj][m][n] = __builtin_amdgcn_mfma_f32_16x16x32_bf16(Bt[n][k], At[m][k], acc[ai][bj][m][n], 0, 0, 0); __builtin_amdgcn_s_setprio(0); } while (0)
; #define PG8_WAIT_V(n) asm volatile("s_waitcnt vmcnt(" #n ")" ::: "memory")
; #define PG8_WAIT_L(n) asm volatile("s_waitcnt lgkmcnt(" #n ")" ::: "memory")
; #define PG8_BAR __builtin_amdgcn_s_barrier()
; #define PG8_SCHED __builtin_amdgcn_sched_barrier(0)
; template <class Epi, class Sched>
; __device__ __forceinline__ void gemm_phase(LAS unsigned char* lds, const int tid, const Gemm g, const Sched& S, const Epi& E) {
;     ...
;             PG8_LDB(B0, 1, 0); PG8_LDB(B1, 1, 1); PG8_SCHED; PG8_LDA(At, 1, 0); PG8_STAGE(PG8_SA(0, 1), a2 + hstep, voffA);
;             PG8_WAIT_V(8); PG8_WAIT_L(0); PG8_BAR; PG8_MMA(0, 0, At, B0); PG8_MMA(0, 1, At, B1); PG8_BAR; PG8_SCHED;
;             PG8_LDA(At, 1, 1); PG8_STAGE(PG8_SB(1, 0), b3, voffB); PG8_STAGE(PG8_SB(1, 1), b3 + hstep, voffB); PG8_STAGE(PG8_SA(1, 0), a3, voffA);
;             PG8_WAIT_V(8); PG8_WAIT_L(0); PG8_BAR; PG8_MMA(1, 0, At, B0); PG8_MMA(1, 1, At, B1); PG8_BAR; PG8_SCHED;
;         }
;         if (wr == 0) PG8_BAR;
	s_setprio 0
	s_add_i32 s29, 0, 0x18000
	s_add_i32 s30, 0, 0x1c000
	s_add_u32 s54, s72, 0x40000
	s_addc_u32 s55, s73, 0
	s_mov_b32 m0, s45
	global_load_lds_dwordx4 v154, s[54:55]
	s_mov_b32 m0, s46
	s_nop 0
	global_load_lds_dwordx4 v156, s[54:55]
	v_add_u32_e32 v142, s29, v177
	v_add_u32_e32 v168, s30, v177
	ds_read_b128 v[130:133], v142
	ds_read_b128 v[134:137], v142 offset:1024
	ds_read_b128 v[138:141], v142 offset:2048
	ds_read_b128 v[142:145], v142 offset:3072
	ds_read_b128 v[146:149], v168
	ds_read_b128 v[150:153], v168 offset:1024
	ds_read_b128 v[164:167], v168 offset:2048
	ds_read_b128 v[168:171], v168 offset:3072
	ds_read_b128 v[172:175], v181 offset:32768
	ds_read_b128 v[182:185], v181 offset:33792
	ds_read_b128 v[186:189], v181 offset:34816
	ds_read_b128 v[190:193], v181 offset:35840
	ds_read_b128 v[204:207], v181 offset:36864
	ds_read_b128 v[208:211], v181 offset:37888
	ds_read_b128 v[212:215], v181 offset:38912
	ds_read_b128 v[216:219], v181 offset:39936
	s_waitcnt vmcnt(8)
	s_waitcnt lgkmcnt(0)
	s_setprio 1
	s_barrier
	v_mfma_f32_16x16x32_bf16 v[126:129], v[130:133], v[172:175], v[126:129]
	v_mfma_f32_16x16x32_bf16 v[122:125], v[138:141], v[172:175], v[122:125]
	v_mfma_f32_16x16x32_bf16 v[110:113], v[130:133], v[186:189], v[110:113]
	v_mfma_f32_16x16x32_bf16 v[106:109], v[138:141], v[186:189], v[106:109]
	v_mfma_f32_16x16x32_bf16 v[94:97], v[130:133], v[204:207], v[94:97]
	v_mfma_f32_16x16x32_bf16 v[90:93], v[138:141], v[204:207], v[90:93]
	v_mfma_f32_16x16x32_bf16 v[78:81], v[130:133], v[212:215], v[78:81]
	v_mfma_f32_16x16x32_bf16 v[74:77], v[138:141], v[212:215], v[74:77]
	v_mfma_f32_16x16x32_bf16 v[126:129], v[134:137], v[182:185], v[126:129]
	v_mfma_f32_16x16x32_bf16 v[122:125], v[142:145], v[182:185], v[122:125]
	v_mfma_f32_16x16x32_bf16 v[110:113], v[134:137], v[190:193], v[110:113]
	v_mfma_f32_16x16x32_bf16 v[106:109], v[142:145], v[190:193], v[106:109]
	v_mfma_f32_16x16x32_bf16 v[94:97], v[134:137], v[208:211], v[94:97]
	v_mfma_f32_16x16x32_bf16 v[90:93], v[142:145], v[208:211], v[90:93]
	v_mfma_f32_16x16x32_bf16 v[78:81], v[134:137], v[216:219], v[78:81]
	v_mfma_f32_16x16x32_bf16 v[74:77], v[142:145], v[216:219], v[74:77]
	s_setprio 0
	s_setprio 1
	v_mfma_f32_16x16x32_bf16 v[118:121], v[146:149], v[172:175], v[118:121]
	v_mfma_f32_16x16x32_bf16 v[114:117], v[164:167], v[172:175], v[114:117]
	v_mfma_f32_16x16x32_bf16 v[102:105], v[146:149], v[186:189], v[102:105]
	v_mfma_f32_16x16x32_bf16 v[98:101], v[164:167], v[186:189], v[98:101]
	v_mfma_f32_16x16x32_bf16 v[86:89], v[146:149], v[204:207], v[86:89]
	v_mfma_f32_16x16x32_bf16 v[82:85], v[164:167], v[204:207], v[82:85]
	v_mfma_f32_16x16x32_bf16 v[70:73], v[146:149], v[212:215], v[70:73]
	v_mfma_f32_16x16x32_bf16 v[66:69], v[164:167], v[212:215], v[66:69]
	v_mfma_f32_16x16x32_bf16 v[118:121], v[150:153], v[182:185], v[118:121]
	v_mfma_f32_16x16x32_bf16 v[114:117], v[168:171], v[182:185], v[114:117]
	v_mfma_f32_16x16x32_bf16 v[102:105], v[150:153], v[190:193], v[102:105]
	v_mfma_f32_16x16x32_bf16 v[98:101], v[168:171], v[190:193], v[98:101]
	v_mfma_f32_16x16x32_bf16 v[86:89], v[150:153], v[208:211], v[86:89]
	v_mfma_f32_16x16x32_bf16 v[82:85], v[168:171], v[208:211], v[82:85]
	v_mfma_f32_16x16x32_bf16 v[70:73], v[150:153], v[216:219], v[70:73]
	v_mfma_f32_16x16x32_bf16 v[66:69], v[168:171], v[216:219], v[66:69]
	s_barrier
	s_setprio 0
	s_add_i32 s29, s29, s15
	s_mov_b32 m0, s29
	ds_read_b128 v[172:175], v181 offset:49152
	global_load_lds_dwordx4 v195, s[20:21]
	s_add_i32 m0, s29, 0x2000
	s_add_i32 s29, s30, s15
	global_load_lds_dwordx4 v201, s[20:21]
	s_add_u32 s20, s20, 0x40080
	s_addc_u32 s21, s21, 0
	s_mov_b32 m0, s29
	s_nop 0
	global_load_lds_dwordx4 v0, s[20:21]
	s_add_i32 m0, s29, 0x2000
	s_nop 0
	global_load_lds_dwordx4 v158, s[20:21]
	s_mov_b32 m0, s12
	s_nop 0
	global_load_lds_dwordx4 v221, s[72:73]
	s_mov_b32 m0, s47
	s_nop 0
	global_load_lds_dwordx4 v223, s[72:73]
	ds_read_b128 v[182:185], v181 offset:50176
	ds_read_b128 v[186:189], v181 offset:51200
	ds_read_b128 v[190:193], v181 offset:52224
	ds_read_b128 v[204:207], v181 offset:53248
	ds_read_b128 v[208:211], v181 offset:54272
	ds_read_b128 v[212:215], v181 offset:55296
	ds_read_b128 v[216:219], v181 offset:56320
	s_waitcnt vmcnt(8)
	s_waitcnt lgkmcnt(0)
	s_setprio 1
	s_barrier
	v_mfma_f32_16x16x32_bf16 v[62:65], v[130:133], v[172:175], v[62:65]
	v_mfma_f32_16x16x32_bf16 v[58:61], v[138:141], v[172:175], v[58:61]
	v_mfma_f32_16x16x32_bf16 v[46:49], v[130:133], v[186:189], v[46:49]
	v_mfma_f32_16x16x32_bf16 v[42:45], v[138:141], v[186:189], v[42:45]
	v_mfma_f32_16x16x32_bf16 v[30:33], v[130:133], v[204:207], v[30:33]
	v_mfma_f32_16x16x32_bf16 v[26:29], v[138:141], v[204:207], v[26:29]
	v_mfma_f32_16x16x32_bf16 v[14:17], v[130:133], v[212:215], v[14:17]
	v_mfma_f32_16x16x32_bf16 v[10:13], v[138:141], v[212:215], v[10:13]
	v_mfma_f32_16x16x32_bf16 v[62:65], v[134:137], v[182:185], v[62:65]
	v_mfma_f32_16x16x32_bf16 v[58:61], v[142:145], v[182:185], v[58:61]
	v_mfma_f32_16x16x32_bf16 v[46:49], v[134:137], v[190:193], v[46:49]
	v_mfma_f32_16x16x32_bf16 v[42:45], v[142:145], v[190:193], v[42:45]
	v_mfma_f32_16x16x32_bf16 v[30:33], v[134:137], v[208:211], v[30:33]
	v_mfma_f32_16x16x32_bf16 v[26:29], v[142:145], v[208:211], v[26:29]
	v_mfma_f32_16x16x32_bf16 v[14:17], v[134:137], v[216:219], v[14:17]
	v_mfma_f32_16x16x32_bf16 v[10:13], v[142:145], v[216:219], v[10:13]
	s_setprio 0
	s_setprio 1
	v_mfma_f32_16x16x32_bf16 v[54:57], v[146:149], v[172:175], v[54:57]
	v_mfma_f32_16x16x32_bf16 v[50:53], v[164:167], v[172:175], v[50:53]
	v_mfma_f32_16x16x32_bf16 v[38:41], v[146:149], v[186:189], v[38:41]
	v_mfma_f32_16x16x32_bf16 v[34:37], v[164:167], v[186:189], v[34:37]
	v_mfma_f32_16x16x32_bf16 v[22:25], v[146:149], v[204:207], v[22:25]
	v_mfma_f32_16x16x32_bf16 v[18:21], v[164:167], v[204:207], v[18:21]
	v_mfma_f32_16x16x32_bf16 v[6:9], v[146:149], v[212:215], v[6:9]
	v_mfma_f32_16x16x32_bf16 v[2:5], v[164:167], v[212:215], v[2:5]
	v_mfma_f32_16x16x32_bf16 v[54:57], v[150:153], v[182:185], v[54:57]
	v_mfma_f32_16x16x32_bf16 v[50:53], v[168:171], v[182:185], v[50:53]
	v_mfma_f32_16x16x32_bf16 v[38:41], v[150:153], v[190:193], v[38:41]
	v_mfma_f32_16x16x32_bf16 v[34:37], v[168:171], v[190:193], v[34:37]
	v_mfma_f32_16x16x32_bf16 v[22:25], v[150:153], v[208:211], v[22:25]
	v_mfma_f32_16x16x32_bf16 v[18:21], v[168:171], v[208:211], v[18:21]
	v_mfma_f32_16x16x32_bf16 v[6:9], v[150:153], v[216:219], v[6:9]
	v_mfma_f32_16x16x32_bf16 v[2:5], v[168:171], v[216:219], v[2:5]
	s_barrier
	s_setprio 0
	s_add_i32 s53, s53, 2
	s_add_u32 s51, s51, 0x100
	s_addc_u32 s52, s52, 0
	s_add_u32 s92, s92, 0x100
	s_addc_u32 s93, s93, 0
	s_cmp_gt_u32 s53, 13
	s_cbranch_scc0 .LBB0_397
	s_and_b64 vcc, exec, s[10:11]
	s_cbranch_vccz .LBB0_400
	s_barrier

; #define PG8_STAGE(bufoff, gbase, voff) do { _Pragma("unroll") for (int _i = 0; _i < 2; ++_i) \
;         __builtin_amdgcn_global_load_lds((const gunsigned*)((const gchar*)(gbase) + (voff)[_i]), (LAS unsigned*)(lds + (bufoff) + ldsw + _i * 8192), 16, 0, 0); } while (0)
; #define PG8_LDA(dst, b, h) do { _Pragma("unroll") for (int m = 0; m < 4; ++m) _Pragma("unroll") for (int k = 0; k < 2; ++k) dst[m][k] = *(const LAS bf16x8*)(lds + PG8_SA(b, h) + aoff + m * 2048 + k * 1024); } while (0)
; #define PG8_LDB(dst, b, h) do { _Pragma("unroll") for (int n = 0; n < 2; ++n) _Pragma("unroll") for (int k = 0; k < 2; ++k) dst[n][k] = *(const LAS bf16x8*)(lds + PG8_SB(b, h) + boff + n * 2048 + k * 1024); } while (0)
; #define PG8_MMA(ai, bj, At, Bt) do { __builtin_amdgcn_s_setprio(1); _Pragma("unroll") for (int m = 0; m < 4; ++m) _Pragma("unroll") for (int n = 0; n < 2; ++n) _Pragma("unroll") for (int k = 0; k < 2; ++k) \
;         acc[ai][bj][m][n] = __builtin_amdgcn_mfma_f32_16x16x32_bf16(Bt[n][k], At[m][k], acc[ai][bj][m][n], 0, 0, 0); __builtin_amdgcn_s_setprio(0); } while (0)
; #define PG8_WAIT_V(n) asm volatile("s_waitcnt vmcnt(" #n ")" ::: "memory")
; #define PG8_WAIT_L(n) asm volatile("s_waitcnt lgkmcnt(" #n ")" ::: "memory")
; #define PG8_BAR __builtin_amdgcn_s_barrier()
; #define PG8_SCHED __builtin_amdgcn_sched_barrier(0)
; template <class Epi, class Sched>
; __device__ __forceinline__ void gemm_phase(LAS unsigned char* lds, const int tid, const Gemm g, const Sched& S, const Epi& E) {
;     ...
;             const gchar* a1 = cA + (size_t)(t + 1) * kstep;
;             const gchar* a2 = last ? nA : cA + (size_t)(t + 2) * kstep; const gchar* b2 = last ? nB : cB + (size_t)(t + 2) * kstep;
;             const gchar* a3 = a2 + kstep; const gchar* b3 = b2 + kstep;
;             PG8_LDB(B0, 0, 0); PG8_LDB(B1, 0, 1); PG8_SCHED; PG8_LDA(At, 0, 0); PG8_STAGE(PG8_SA(1, 1), a1 + hstep, voffA);
;             PG8_WAIT_V(8); PG8_WAIT_L(0); PG8_BAR; PG8_MMA(0, 0, At, B0); PG8_MMA(0, 1, At, B1); PG8_BAR; PG8_SCHED;
;             PG8_LDA(At, 0, 1); PG8_STAGE(PG8_SB(0, 0), b2, voffB); PG8_STAGE(PG8_SB(0, 1), b2 + hstep, voffB); PG8_STAGE(PG8_SA(0, 0), a2, voffA);
;             PG8_WAIT_V(8); PG8_WAIT_L(0); PG8_BAR; PG8_MMA(1, 0, At, B0); PG8_MMA(1, 1, At, B1); PG8_BAR; PG8_SCHED;
.LBB0_444:
	s_add_u32 s20, s16, 0xfffe0080
	s_addc_u32 s21, s17, -1
	s_add_i32 s29, 0, 0x10000
	s_cmp_eq_u32 s51, 4
	s_cselect_b32 s73, s1, s21
	s_cselect_b32 s72, s5, s20
	s_cselect_b32 s21, s15, s31
	s_cselect_b32 s20, s23, s24
	s_add_i32 s30, 0, 0x14000
	s_add_i32 m0, s93, 0xc000
	global_load_lds_dwordx4 v212, s[16:17]
	s_add_i32 m0, s93, 0xe000
	s_nop 0
	global_load_lds_dwordx4 v210, s[16:17]
	v_add_u32_e32 v122, s29, v242
	ds_read_b128 v[132:135], v122
	ds_read_b128 v[136:139], v122 offset:1024
	ds_read_b128 v[140:143], v122 offset:2048
	ds_read_b128 v[144:147], v122 offset:3072
	v_add_u32_e32 v122, s30, v242
	ds_read_b128 v[148:151], v122
	ds_read_b128 v[152:155], v122 offset:1024
	ds_read_b128 v[156:159], v122 offset:2048
	ds_read_b128 v[160:163], v122 offset:3072
	ds_read_b128 v[164:167], v244
	ds_read_b128 v[168:171], v244 offset:1024
	ds_read_b128 v[172:175], v244 offset:2048
	ds_read_b128 v[176:179], v244 offset:3072
	ds_read_b128 v[180:183], v244 offset:4096
	ds_read_b128 v[184:187], v244 offset:5120
	ds_read_b128 v[188:191], v244 offset:6144
	ds_read_b128 v[192:195], v244 offset:7168
	s_waitcnt vmcnt(8)
	s_waitcnt lgkmcnt(0)
	s_setprio 1
	s_barrier
	v_mfma_f32_16x16x32_bf16 v[128:131], v[132:135], v[164:167], v[128:131]
	v_mfma_f32_16x16x32_bf16 v[122:125], v[140:143], v[164:167], v[124:127]
	v_mfma_f32_16x16x32_bf16 v[110:113], v[132:135], v[172:175], v[110:113]
	v_mfma_f32_16x16x32_bf16 v[106:109], v[140:143], v[172:175], v[106:109]
	v_mfma_f32_16x16x32_bf16 v[94:97], v[132:135], v[180:183], v[94:97]
	v_mfma_f32_16x16x32_bf16 v[90:93], v[140:143], v[180:183], v[90:93]
	v_mfma_f32_16x16x32_bf16 v[78:81], v[132:135], v[188:191], v[78:81]
	v_mfma_f32_16x16x32_bf16 v[74:77], v[140:143], v[188:191], v[74:77]
	v_mfma_f32_16x16x32_bf16 v[128:131], v[136:139], v[168:171], v[128:131]
	v_mfma_f32_16x16x32_bf16 v[122:125], v[144:147], v[168:171], v[122:125]
	v_mfma_f32_16x16x32_bf16 v[110:113], v[136:139], v[176:179], v[110:113]
	v_mfma_f32_16x16x32_bf16 v[106:109], v[144:147], v[176:179], v[106:109]
	v_mfma_f32_16x16x32_bf16 v[94:97], v[136:139], v[184:187], v[94:97]
	v_mfma_f32_16x16x32_bf16 v[90:93], v[144:147], v[184:187], v[90:93]
	v_mfma_f32_16x16x32_bf16 v[78:81], v[136:139], v[192:195], v[78:81]
	v_mfma_f32_16x16x32_bf16 v[74:77], v[144:147], v[192:195], v[74:77]
	s_setprio 0
	s_setprio 1
	v_mfma_f32_16x16x32_bf16 v[118:121], v[148:151], v[164:167], v[118:121]
	v_mfma_f32_16x16x32_bf16 v[114:117], v[156:159], v[164:167], v[114:117]
	v_mfma_f32_16x16x32_bf16 v[102:105], v[148:151], v[172:175], v[102:105]
	v_mfma_f32_16x16x32_bf16 v[98:101], v[156:159], v[172:175], v[98:101]
	v_mfma_f32_16x16x32_bf16 v[86:89], v[148:151], v[180:183], v[86:89]
	v_mfma_f32_16x16x32_bf16 v[82:85], v[156:159], v[180:183], v[82:85]
	v_mfma_f32_16x16x32_bf16 v[70:73], v[148:151], v[188:191], v[70:73]
	v_mfma_f32_16x16x32_bf16 v[66:69], v[156:159], v[188:191], v[66:69]
	v_mfma_f32_16x16x32_bf16 v[118:121], v[152:155], v[168:171], v[118:121]
	v_mfma_f32_16x16x32_bf16 v[114:117], v[160:163], v[168:171], v[114:117]
	v_mfma_f32_16x16x32_bf16 v[102:105], v[152:155], v[176:179], v[102:105]
	v_mfma_f32_16x16x32_bf16 v[98:101], v[160:163], v[176:179], v[98:101]
	v_mfma_f32_16x16x32_bf16 v[86:89], v[152:155], v[184:187], v[86:89]
	v_mfma_f32_16x16x32_bf16 v[82:85], v[160:163], v[184:187], v[82:85]
	v_mfma_f32_16x16x32_bf16 v[70:73], v[152:155], v[192:195], v[70:73]
	v_mfma_f32_16x16x32_bf16 v[66:69], v[160:163], v[192:195], v[66:69]
	s_barrier
	s_setprio 0
	s_add_i32 s29, s29, s42
	s_mov_b32 m0, s29
	global_load_lds_dwordx4 v0, s[20:21]
	s_add_i32 m0, s29, 0x2000
	s_add_u32 s52, s20, 0x20000
	s_addc_u32 s53, s21, 0
	s_add_i32 s29, s30, s42
	global_load_lds_dwordx4 v208, s[20:21]
	s_mov_b32 m0, s29
	s_nop 0
	global_load_lds_dwordx4 v0, s[52:53]
	s_add_i32 m0, s29, 0x2000
	s_nop 0
	global_load_lds_dwordx4 v208, s[52:53]
	s_mov_b32 m0, s93
	s_nop 0
	global_load_lds_dwordx4 v204, s[72:73]
	s_mov_b32 m0, s44
	s_nop 0
	global_load_lds_dwordx4 v206, s[72:73]
	ds_read_b128 v[164:167], v244 offset:16384
	ds_read_b128 v[168:171], v244 offset:17408
	ds_read_b128 v[172:175], v244 offset:18432
	ds_read_b128 v[176:179], v244 offset:19456
	ds_read_b128 v[180:183], v244 offset:20480
	ds_read_b128 v[184:187], v244 offset:21504
	ds_read_b128 v[188:191], v244 offset:22528
	ds_read_b128 v[192:195], v244 offset:23552
	s_waitcnt vmcnt(8)
	s_waitcnt lgkmcnt(0)
	s_setprio 1
	s_barrier
	v_mfma_f32_16x16x32_bf16 v[62:65], v[132:135], v[164:167], v[62:65]
	v_mfma_f32_16x16x32_bf16 v[58:61], v[140:143], v[164:167], v[58:61]
	v_mfma_f32_16x16x32_bf16 v[46:49], v[132:135], v[172:175], v[46:49]
	v_mfma_f32_16x16x32_bf16 v[42:45], v[140:143], v[172:175], v[42:45]
	v_mfma_f32_16x16x32_bf16 v[30:33], v[132:135], v[180:183], v[30:33]
	v_mfma_f32_16x16x32_bf16 v[26:29], v[140:143], v[180:183], v[26:29]
	v_mfma_f32_16x16x32_bf16 v[14:17], v[132:135], v[188:191], v[14:17]
	v_mfma_f32_16x16x32_bf16 v[10:13], v[140:143], v[188:191], v[10:13]
	v_mfma_f32_16x16x32_bf16 v[62:65], v[136:139], v[168:171], v[62:65]
	v_mfma_f32_16x16x32_bf16 v[58:61], v[144:147], v[168:171], v[58:61]
	v_mfma_f32_16x16x32_bf16 v[46:49], v[136:139], v[176:179], v[46:49]
	v_mfma_f32_16x16x32_bf16 v[42:45], v[144:147], v[176:179], v[42:45]
	v_mfma_f32_16x16x32_bf16 v[30:33], v[136:139], v[184:187], v[30:33]
	v_mfma_f32_16x16x32_bf16 v[26:29], v[144:147], v[184:187], v[26:29]
	v_mfma_f32_16x16x32_bf16 v[14:17], v[136:139], v[192:195], v[14:17]
	v_mfma_f32_16x16x32_bf16 v[10:13], v[144:147], v[192:195], v[10:13]
	s_setprio 0
	s_setprio 1
	v_mfma_f32_16x16x32_bf16 v[54:57], v[148:151], v[164:167], v[54:57]
	v_mfma_f32_16x16x32_bf16 v[50:53], v[156:159], v[164:167], v[50:53]
	v_mfma_f32_16x16x32_bf16 v[38:41], v[148:151], v[172:175], v[38:41]
	v_mfma_f32_16x16x32_bf16 v[34:37], v[156:159], v[172:175], v[34:37]
	v_mfma_f32_16x16x32_bf16 v[22:25], v[148:151], v[180:183], v[22:25]
	v_mfma_f32_16x16x32_bf16 v[18:21], v[156:159], v[180:183], v[18:21]
	v_mfma_f32_16x16x32_bf16 v[6:9], v[148:151], v[188:191], v[6:9]
	v_mfma_f32_16x16x32_bf16 v[2:5], v[156:159], v[188:191], v[2:5]
	v_mfma_f32_16x16x32_bf16 v[54:57], v[152:155], v[168:171], v[54:57]
	v_mfma_f32_16x16x32_bf16 v[50:53], v[160:163], v[168:171], v[50:53]
	v_mfma_f32_16x16x32_bf16 v[38:41], v[152:155], v[176:179], v[38:41]
	v_mfma_f32_16x16x32_bf16 v[34:37], v[160:163], v[176:179], v[34:37]
	v_mfma_f32_16x16x32_bf16 v[22:25], v[152:155], v[184:187], v[22:25]
	v_mfma_f32_16x16x32_bf16 v[18:21], v[160:163], v[184:187], v[18:21]
	v_mfma_f32_16x16x32_bf16 v[6:9], v[152:155], v[192:195], v[6:9]
	v_mfma_f32_16x16x32_bf16 v[2:5], v[160:163], v[192:195], v[2:5]
	s_barrier
; #define PG8_STAGE(bufoff, gbase, voff) do { _Pragma("unroll") for (int _i = 0; _i < 2; ++_i) \
;         __builtin_amdgcn_global_load_lds((const gunsigned*)((const gchar*)(gbase) + (voff)[_i]), (LAS unsigned*)(lds + (bufoff) + ldsw + _i * 8192), 16, 0, 0); } while (0)
; #define PG8_LDA(dst, b, h) do { _Pragma("unroll") for (int m = 0; m < 4; ++m) _Pragma("unroll") for (int k = 0; k < 2; ++k) dst[m][k] = *(const LAS bf16x8*)(lds + PG8_SA(b, h) + aoff + m * 2048 + k * 1024); } while (0)
; #define PG8_LDB(dst, b, h) do { _Pragma("unroll") for (int n = 0; n < 2; ++n) _Pragma("unroll") for (int k = 0; k < 2; ++k) dst[n][k] = *(const LAS bf16x8*)(lds + PG8_SB(b, h) + boff + n * 2048 + k * 1024); } while (0)
; #define PG8_MMA(ai, bj, At, Bt) do { __builtin_amdgcn_s_setprio(1); _Pragma("unroll") for (int m = 0; m < 4; ++m) _Pragma("unroll") for (int n = 0; n < 2; ++n) _Pragma("unroll") for (int k = 0; k < 2; ++k) \
;         acc[ai][bj][m][n] = __builtin_amdgcn_mfma_f32_16x16x32_bf16(Bt[n][k], At[m][k], acc[ai][bj][m][n], 0, 0, 0); __builtin_amdgcn_s_setprio(0); } while (0)
; #define PG8_WAIT_V(n) asm volatile("s_waitcnt vmcnt(" #n ")" ::: "memory")
; #define PG8_WAIT_L(n) asm volatile("s_waitcnt lgkmcnt(" #n ")" ::: "memory")
; #define PG8_BAR __builtin_amdgcn_s_barrier()
; #define PG8_SCHED __builtin_amdgcn_sched_barrier(0)
; template <class Epi, class Sched>
; __device__ __forceinline__ void gemm_phase(LAS unsigned char* lds, const int tid, const Gemm g, const Sched& S, const Epi& E) {
;     ...
;             PG8_LDB(B0, 1, 0); PG8_LDB(B1, 1, 1); PG8_SCHED; PG8_LDA(At, 1, 0); PG8_STAGE(PG8_SA(0, 1), a2 + hstep, voffA);
;             PG8_WAIT_V(8); PG8_WAIT_L(0); PG8_BAR; PG8_MMA(0, 0, At, B0); PG8_MMA(0, 1, At, B1); PG8_BAR; PG8_SCHED;
;             PG8_LDA(At, 1, 1); PG8_STAGE(PG8_SB(1, 0), b3, voffB); PG8_STAGE(PG8_SB(1, 1), b3 + hstep, voffB); PG8_STAGE(PG8_SA(1, 0), a3, voffA);
;             PG8_WAIT_V(8); PG8_WAIT_L(0); PG8_BAR; PG8_MMA(1, 0, At, B0); PG8_MMA(1, 1, At, B1); PG8_BAR; PG8_SCHED;
;         }
;         if (wr == 0) PG8_BAR;
	s_setprio 0
	s_add_i32 s29, 0, 0x18000
	v_add_u32_e32 v126, s29, v242
	s_add_i32 s30, 0, 0x1c000
	s_add_u32 s52, s72, 0x20000
	s_addc_u32 s53, s73, 0
	s_mov_b32 m0, s45
	global_load_lds_dwordx4 v204, s[52:53]
	s_mov_b32 m0, s46
	s_nop 0
	global_load_lds_dwordx4 v206, s[52:53]
	ds_read_b128 v[132:135], v126
	ds_read_b128 v[136:139], v126 offset:1024
	ds_read_b128 v[140:143], v126 offset:2048
	ds_read_b128 v[144:147], v126 offset:3072
	v_add_u32_e32 v126, s30, v242
	ds_read_b128 v[148:151], v126
	ds_read_b128 v[152:155], v126 offset:1024
	ds_read_b128 v[156:159], v126 offset:2048
	ds_read_b128 v[160:163], v126 offset:3072
	ds_read_b128 v[164:167], v244 offset:32768
	ds_read_b128 v[168:171], v244 offset:33792
	ds_read_b128 v[172:175], v244 offset:34816
	ds_read_b128 v[176:179], v244 offset:35840
	ds_read_b128 v[180:183], v244 offset:36864
	ds_read_b128 v[184:187], v244 offset:37888
	ds_read_b128 v[188:191], v244 offset:38912
	ds_read_b128 v[192:195], v244 offset:39936
	s_waitcnt vmcnt(8)
	s_waitcnt lgkmcnt(0)
	s_setprio 1
	s_barrier
	v_mfma_f32_16x16x32_bf16 v[126:129], v[132:135], v[164:167], v[128:131]
	v_mfma_f32_16x16x32_bf16 v[122:125], v[140:143], v[164:167], v[122:125]
	v_mfma_f32_16x16x32_bf16 v[110:113], v[132:135], v[172:175], v[110:113]
	v_mfma_f32_16x16x32_bf16 v[106:109], v[140:143], v[172:175], v[106:109]
	v_mfma_f32_16x16x32_bf16 v[94:97], v[132:135], v[180:183], v[94:97]
	v_mfma_f32_16x16x32_bf16 v[90:93], v[140:143], v[180:183], v[90:93]
	v_mfma_f32_16x16x32_bf16 v[78:81], v[132:135], v[188:191], v[78:81]
	v_mfma_f32_16x16x32_bf16 v[74:77], v[140:143], v[188:191], v[74:77]
	v_mfma_f32_16x16x32_bf16 v[128:131], v[136:139], v[168:171], v[126:129]
	v_mfma_f32_16x16x32_bf16 v[124:127], v[144:147], v[168:171], v[122:125]
	v_mfma_f32_16x16x32_bf16 v[110:113], v[136:139], v[176:179], v[110:113]
	v_mfma_f32_16x16x32_bf16 v[106:109], v[144:147], v[176:179], v[106:109]
	v_mfma_f32_16x16x32_bf16 v[94:97], v[136:139], v[184:187], v[94:97]
	v_mfma_f32_16x16x32_bf16 v[90:93], v[144:147], v[184:187], v[90:93]
	v_mfma_f32_16x16x32_bf16 v[78:81], v[136:139], v[192:195], v[78:81]
	v_mfma_f32_16x16x32_bf16 v[74:77], v[144:147], v[192:195], v[74:77]
	s_setprio 0
	s_setprio 1
	v_mfma_f32_16x16x32_bf16 v[118:121], v[148:151], v[164:167], v[118:121]
	v_mfma_f32_16x16x32_bf16 v[114:117], v[156:159], v[164:167], v[114:117]
	v_mfma_f32_16x16x32_bf16 v[102:105], v[148:151], v[172:175], v[102:105]
	v_mfma_f32_16x16x32_bf16 v[98:101], v[156:159], v[172:175], v[98:101]
	v_mfma_f32_16x16x32_bf16 v[86:89], v[148:151], v[180:183], v[86:89]
	v_mfma_f32_16x16x32_bf16 v[82:85], v[156:159], v[180:183], v[82:85]
	v_mfma_f32_16x16x32_bf16 v[70:73], v[148:151], v[188:191], v[70:73]
	v_mfma_f32_16x16x32_bf16 v[66:69], v[156:159], v[188:191], v[66:69]
	v_mfma_f32_16x16x32_bf16 v[118:121], v[152:155], v[168:171], v[118:121]
	v_mfma_f32_16x16x32_bf16 v[114:117], v[160:163], v[168:171], v[114:117]
	v_mfma_f32_16x16x32_bf16 v[102:105], v[152:155], v[176:179], v[102:105]
	v_mfma_f32_16x16x32_bf16 v[98:101], v[160:163], v[176:179], v[98:101]
	v_mfma_f32_16x16x32_bf16 v[86:89], v[152:155], v[184:187], v[86:89]
	v_mfma_f32_16x16x32_bf16 v[82:85], v[160:163], v[184:187], v[82:85]
	v_mfma_f32_16x16x32_bf16 v[70:73], v[152:155], v[192:195], v[70:73]
	v_mfma_f32_16x16x32_bf16 v[66:69], v[160:163], v[192:195], v[66:69]
	s_barrier
	s_setprio 0
	s_add_i32 s29, s29, s42
	s_mov_b32 m0, s29
	ds_read_b128 v[164:167], v244 offset:49152
	global_load_lds_dwordx4 v201, s[20:21]
	s_add_i32 m0, s29, 0x2000
	s_add_i32 s29, s30, s42
	global_load_lds_dwordx4 v215, s[20:21]
	s_add_u32 s20, s20, 0x20080
	s_addc_u32 s21, s21, 0
	s_mov_b32 m0, s29
	s_nop 0
	global_load_lds_dwordx4 v0, s[20:21]
	s_add_i32 m0, s29, 0x2000
	s_nop 0
	global_load_lds_dwordx4 v208, s[20:21]
	s_mov_b32 m0, s47
	s_nop 0
	global_load_lds_dwordx4 v217, s[72:73]
	s_mov_b32 m0, s48
	s_nop 0
	global_load_lds_dwordx4 v219, s[72:73]
	ds_read_b128 v[168:171], v244 offset:50176
	ds_read_b128 v[172:175], v244 offset:51200
	ds_read_b128 v[176:179], v244 offset:52224
	ds_read_b128 v[180:183], v244 offset:53248
	ds_read_b128 v[184:187], v244 offset:54272
	ds_read_b128 v[188:191], v244 offset:55296
	ds_read_b128 v[192:195], v244 offset:56320
	s_waitcnt vmcnt(8)
	s_waitcnt lgkmcnt(0)
	s_setprio 1
	s_barrier
	v_mfma_f32_16x16x32_bf16 v[62:65], v[132:135], v[164:167], v[62:65]
	v_mfma_f32_16x16x32_bf16 v[58:61], v[140:143], v[164:167], v[58:61]
	v_mfma_f32_16x16x32_bf16 v[46:49], v[132:135], v[172:175], v[46:49]
	v_mfma_f32_16x16x32_bf16 v[42:45], v[140:143], v[172:175], v[42:45]
	v_mfma_f32_16x16x32_bf16 v[30:33], v[132:135], v[180:183], v[30:33]
	v_mfma_f32_16x16x32_bf16 v[26:29], v[140:143], v[180:183], v[26:29]
	v_mfma_f32_16x16x32_bf16 v[14:17], v[132:135], v[188:191], v[14:17]
	v_mfma_f32_16x16x32_bf16 v[10:13], v[140:143], v[188:191], v[10:13]
	v_mfma_f32_16x16x32_bf16 v[62:65], v[136:139], v[168:171], v[62:65]
	v_mfma_f32_16x16x32_bf16 v[58:61], v[144:147], v[168:171], v[58:61]
	v_mfma_f32_16x16x32_bf16 v[46:49], v[136:139], v[176:179], v[46:49]
	v_mfma_f32_16x16x32_bf16 v[42:45], v[144:147], v[176:179], v[42:45]
	v_mfma_f32_16x16x32_bf16 v[30:33], v[136:139], v[184:187], v[30:33]
	v_mfma_f32_16x16x32_bf16 v[26:29], v[144:147], v[184:187], v[26:29]
	v_mfma_f32_16x16x32_bf16 v[14:17], v[136:139], v[192:195], v[14:17]
	v_mfma_f32_16x16x32_bf16 v[10:13], v[144:147], v[192:195], v[10:13]
	s_setprio 0
	s_setprio 1
	v_mfma_f32_16x16x32_bf16 v[54:57], v[148:151], v[164:167], v[54:57]
	v_mfma_f32_16x16x32_bf16 v[50:53], v[156:159], v[164:167], v[50:53]
	v_mfma_f32_16x16x32_bf16 v[38:41], v[148:151], v[172:175], v[38:41]
	v_mfma_f32_16x16x32_bf16 v[34:37], v[156:159], v[172:175], v[34:37]
	v_mfma_f32_16x16x32_bf16 v[22:25], v[148:151], v[180:183], v[22:25]
	v_mfma_f32_16x16x32_bf16 v[18:21], v[156:159], v[180:183], v[18:21]
	v_mfma_f32_16x16x32_bf16 v[6:9], v[148:151], v[188:191], v[6:9]
	v_mfma_f32_16x16x32_bf16 v[2:5], v[156:159], v[188:191], v[2:5]
	v_mfma_f32_16x16x32_bf16 v[54:57], v[152:155], v[168:171], v[54:57]
	v_mfma_f32_16x16x32_bf16 v[50:53], v[160:163], v[168:171], v[50:53]
	v_mfma_f32_16x16x32_bf16 v[38:41], v[152:155], v[176:179], v[38:41]
	v_mfma_f32_16x16x32_bf16 v[34:37], v[160:163], v[176:179], v[34:37]
	v_mfma_f32_16x16x32_bf16 v[22:25], v[152:155], v[184:187], v[22:25]
	v_mfma_f32_16x16x32_bf16 v[18:21], v[160:163], v[184:187], v[18:21]
	v_mfma_f32_16x16x32_bf16 v[6:9], v[152:155], v[192:195], v[6:9]
	v_mfma_f32_16x16x32_bf16 v[2:5], v[160:163], v[192:195], v[2:5]
	s_barrier
	s_setprio 0
	s_add_i32 s51, s51, 2
	s_add_u32 s24, s24, 0x100
	s_addc_u32 s31, s31, 0
	s_add_u32 s16, s16, 0x100
	s_addc_u32 s17, s17, 0
	s_cmp_gt_u32 s51, 5
	s_cbranch_scc0 .LBB0_444
	s_and_b64 vcc, exec, s[10:11]
	s_cbranch_vccz .LBB0_447
	s_barrier

; #define PG8_STAGE(bufoff, gbase, voff) do { _Pragma("unroll") for (int _i = 0; _i < 2; ++_i) \
;         __builtin_amdgcn_global_load_lds((const gunsigned*)((const gchar*)(gbase) + (voff)[_i]), (LAS unsigned*)(lds + (bufoff) + ldsw + _i * 8192), 16, 0, 0); } while (0)
; #define PG8_LDA(dst, b, h) do { _Pragma("unroll") for (int m = 0; m < 4; ++m) _Pragma("unroll") for (int k = 0; k < 2; ++k) dst[m][k] = *(const LAS bf16x8*)(lds + PG8_SA(b, h) + aoff + m * 2048 + k * 1024); } while (0)
; #define PG8_LDB(dst, b, h) do { _Pragma("unroll") for (int n = 0; n < 2; ++n) _Pragma("unroll") for (int k = 0; k < 2; ++k) dst[n][k] = *(const LAS bf16x8*)(lds + PG8_SB(b, h) + boff + n * 2048 + k * 1024); } while (0)
; #define PG8_MMA(ai, bj, At, Bt) do { __builtin_amdgcn_s_setprio(1); _Pragma("unroll") for (int m = 0; m < 4; ++m) _Pragma("unroll") for (int n = 0; n < 2; ++n) _Pragma("unroll") for (int k = 0; k < 2; ++k) \
;         acc[ai][bj][m][n] = __builtin_amdgcn_mfma_f32_16x16x32_bf16(Bt[n][k], At[m][k], acc[ai][bj][m][n], 0, 0, 0); __builtin_amdgcn_s_setprio(0); } while (0)
; #define PG8_WAIT_V(n) asm volatile("s_waitcnt vmcnt(" #n ")" ::: "memory")
; #define PG8_WAIT_L(n) asm volatile("s_waitcnt lgkmcnt(" #n ")" ::: "memory")
; #define PG8_BAR __builtin_amdgcn_s_barrier()
; #define PG8_SCHED __builtin_amdgcn_sched_barrier(0)
; template <class Epi, class Sched>
; __device__ __forceinline__ void gemm_phase(LAS unsigned char* lds, const int tid, const Gemm g, const Sched& S, const Epi& E) {
;     ...
;             const gchar* a1 = cA + (size_t)(t + 1) * kstep;
;             const gchar* a2 = last ? nA : cA + (size_t)(t + 2) * kstep; const gchar* b2 = last ? nB : cB + (size_t)(t + 2) * kstep;
;             const gchar* a3 = a2 + kstep; const gchar* b3 = b2 + kstep;
;             PG8_LDB(B0, 0, 0); PG8_LDB(B1, 0, 1); PG8_SCHED; PG8_LDA(At, 0, 0); PG8_STAGE(PG8_SA(1, 1), a1 + hstep, voffA);
;             PG8_WAIT_V(8); PG8_WAIT_L(0); PG8_BAR; PG8_MMA(0, 0, At, B0); PG8_MMA(0, 1, At, B1); PG8_BAR; PG8_SCHED;
;             PG8_LDA(At, 0, 1); PG8_STAGE(PG8_SB(0, 0), b2, voffB); PG8_STAGE(PG8_SB(0, 1), b2 + hstep, voffB); PG8_STAGE(PG8_SA(0, 0), a2, voffA);
;             PG8_WAIT_V(8); PG8_WAIT_L(0); PG8_BAR; PG8_MMA(1, 0, At, B0); PG8_MMA(1, 1, At, B1); PG8_BAR; PG8_SCHED;
.LBB0_559:
	s_add_u32 s20, s60, 0xfffc0080
	s_addc_u32 s21, s61, -1
	s_add_i32 s29, 0, 0x10000
	s_cmp_eq_u32 s46, 12
	s_cselect_b32 s63, s9, s21
	s_cselect_b32 s62, s42, s20
	s_cselect_b32 s21, s7, s45
	s_cselect_b32 s20, s43, s44
	s_add_i32 s30, 0, 0x14000
	s_add_i32 m0, s34, 0xc000
	global_load_lds_dwordx4 v142, s[60:61]
	s_add_i32 m0, s34, 0xe000
	s_nop 0
	global_load_lds_dwordx4 v140, s[60:61]
	v_add_u32_e32 v152, s29, v165
	v_add_u32_e32 v160, s30, v165
	ds_read_b128 v[130:133], v152
	ds_read_b128 v[144:147], v152 offset:1024
	ds_read_b128 v[148:151], v152 offset:2048
	ds_read_b128 v[152:155], v152 offset:3072
	ds_read_b128 v[156:159], v160
	ds_read_b128 v[170:173], v160 offset:1024
	ds_read_b128 v[174:177], v160 offset:2048
	ds_read_b128 v[178:181], v160 offset:3072
	ds_read_b128 v[182:185], v169
	ds_read_b128 v[186:189], v169 offset:1024
	ds_read_b128 v[190:193], v169 offset:2048
	ds_read_b128 v[204:207], v169 offset:3072
	ds_read_b128 v[210:213], v169 offset:4096
	ds_read_b128 v[214:217], v169 offset:5120
	ds_read_b128 v[218:221], v169 offset:6144
	ds_read_b128 v[222:225], v169 offset:7168
	s_waitcnt vmcnt(8)
	s_waitcnt lgkmcnt(0)
	s_setprio 1
	s_barrier
	v_mfma_f32_16x16x32_bf16 v[126:129], v[130:133], v[182:185], v[126:129]
	v_mfma_f32_16x16x32_bf16 v[122:125], v[148:151], v[182:185], v[122:125]
	v_mfma_f32_16x16x32_bf16 v[118:121], v[130:133], v[190:193], v[118:121]
	v_mfma_f32_16x16x32_bf16 v[110:113], v[148:151], v[190:193], v[110:113]
	v_mfma_f32_16x16x32_bf16 v[102:105], v[130:133], v[210:213], v[102:105]
	v_mfma_f32_16x16x32_bf16 v[94:97], v[148:151], v[210:213], v[94:97]
	v_mfma_f32_16x16x32_bf16 v[86:89], v[130:133], v[218:221], v[86:89]
	v_mfma_f32_16x16x32_bf16 v[78:81], v[148:151], v[218:221], v[78:81]
	v_mfma_f32_16x16x32_bf16 v[126:129], v[144:147], v[186:189], v[126:129]
	v_mfma_f32_16x16x32_bf16 v[122:125], v[152:155], v[186:189], v[122:125]
	v_mfma_f32_16x16x32_bf16 v[118:121], v[144:147], v[204:207], v[118:121]
	v_mfma_f32_16x16x32_bf16 v[110:113], v[152:155], v[204:207], v[110:113]
	v_mfma_f32_16x16x32_bf16 v[102:105], v[144:147], v[214:217], v[102:105]
	v_mfma_f32_16x16x32_bf16 v[94:97], v[152:155], v[214:217], v[94:97]
	v_mfma_f32_16x16x32_bf16 v[86:89], v[144:147], v[222:225], v[86:89]
	v_mfma_f32_16x16x32_bf16 v[78:81], v[152:155], v[222:225], v[78:81]
	s_setprio 0
	s_setprio 1
	v_mfma_f32_16x16x32_bf16 v[114:117], v[156:159], v[182:185], v[114:117]
	v_mfma_f32_16x16x32_bf16 v[106:109], v[174:177], v[182:185], v[106:109]
	v_mfma_f32_16x16x32_bf16 v[98:101], v[156:159], v[190:193], v[98:101]
	v_mfma_f32_16x16x32_bf16 v[90:93], v[174:177], v[190:193], v[90:93]
	v_mfma_f32_16x16x32_bf16 v[82:85], v[156:159], v[210:213], v[82:85]
	v_mfma_f32_16x16x32_bf16 v[74:77], v[174:177], v[210:213], v[74:77]
	v_mfma_f32_16x16x32_bf16 v[70:73], v[156:159], v[218:221], v[70:73]
	v_mfma_f32_16x16x32_bf16 v[66:69], v[174:177], v[218:221], v[66:69]
	v_mfma_f32_16x16x32_bf16 v[114:117], v[170:173], v[186:189], v[114:117]
	v_mfma_f32_16x16x32_bf16 v[106:109], v[178:181], v[186:189], v[106:109]
	v_mfma_f32_16x16x32_bf16 v[98:101], v[170:173], v[204:207], v[98:101]
	v_mfma_f32_16x16x32_bf16 v[90:93], v[178:181], v[204:207], v[90:93]
	v_mfma_f32_16x16x32_bf16 v[82:85], v[170:173], v[214:217], v[82:85]
	v_mfma_f32_16x16x32_bf16 v[74:77], v[178:181], v[214:217], v[74:77]
	v_mfma_f32_16x16x32_bf16 v[70:73], v[170:173], v[222:225], v[70:73]
	v_mfma_f32_16x16x32_bf16 v[66:69], v[178:181], v[222:225], v[66:69]
	s_barrier
	s_setprio 0
	s_add_i32 s29, s29, s12
	s_mov_b32 m0, s29
	global_load_lds_dwordx4 v0, s[20:21]
	s_add_i32 m0, s29, 0x2000
	s_add_u32 s48, s20, 0x40000
	s_addc_u32 s49, s21, 0
	s_add_i32 s29, s30, s12
	global_load_lds_dwordx4 v134, s[20:21]
	s_mov_b32 m0, s29
	s_nop 0
	global_load_lds_dwordx4 v0, s[48:49]
	s_add_i32 m0, s29, 0x2000
	s_nop 0
	global_load_lds_dwordx4 v134, s[48:49]
	s_mov_b32 m0, s34
	s_nop 0
	global_load_lds_dwordx4 v138, s[62:63]
	s_mov_b32 m0, s35
	s_nop 0
	global_load_lds_dwordx4 v136, s[62:63]
	ds_read_b128 v[182:185], v169 offset:16384
	ds_read_b128 v[186:189], v169 offset:17408
	ds_read_b128 v[190:193], v169 offset:18432
	ds_read_b128 v[204:207], v169 offset:19456
	ds_read_b128 v[210:213], v169 offset:20480
	ds_read_b128 v[214:217], v169 offset:21504
	ds_read_b128 v[218:221], v169 offset:22528
	ds_read_b128 v[222:225], v169 offset:23552
	s_waitcnt vmcnt(8)
	s_waitcnt lgkmcnt(0)
	s_setprio 1
	s_barrier
	v_mfma_f32_16x16x32_bf16 v[62:65], v[130:133], v[182:185], v[62:65]
	v_mfma_f32_16x16x32_bf16 v[58:61], v[148:151], v[182:185], v[58:61]
	v_mfma_f32_16x16x32_bf16 v[54:57], v[130:133], v[190:193], v[54:57]
	v_mfma_f32_16x16x32_bf16 v[46:49], v[148:151], v[190:193], v[46:49]
	v_mfma_f32_16x16x32_bf16 v[38:41], v[130:133], v[210:213], v[38:41]
	v_mfma_f32_16x16x32_bf16 v[30:33], v[148:151], v[210:213], v[30:33]
	v_mfma_f32_16x16x32_bf16 v[22:25], v[130:133], v[218:221], v[22:25]
	v_mfma_f32_16x16x32_bf16 v[14:17], v[148:151], v[218:221], v[14:17]
	v_mfma_f32_16x16x32_bf16 v[62:65], v[144:147], v[186:189], v[62:65]
	v_mfma_f32_16x16x32_bf16 v[58:61], v[152:155], v[186:189], v[58:61]
	v_mfma_f32_16x16x32_bf16 v[54:57], v[144:147], v[204:207], v[54:57]
	v_mfma_f32_16x16x32_bf16 v[46:49], v[152:155], v[204:207], v[46:49]
	v_mfma_f32_16x16x32_bf16 v[38:41], v[144:147], v[214:217], v[38:41]
	v_mfma_f32_16x16x32_bf16 v[30:33], v[152:155], v[214:217], v[30:33]
	v_mfma_f32_16x16x32_bf16 v[22:25], v[144:147], v[222:225], v[22:25]
	v_mfma_f32_16x16x32_bf16 v[14:17], v[152:155], v[222:225], v[14:17]
	s_setprio 0
	s_setprio 1
	v_mfma_f32_16x16x32_bf16 v[50:53], v[156:159], v[182:185], v[50:53]
	v_mfma_f32_16x16x32_bf16 v[42:45], v[174:177], v[182:185], v[42:45]
	v_mfma_f32_16x16x32_bf16 v[34:37], v[156:159], v[190:193], v[34:37]
	v_mfma_f32_16x16x32_bf16 v[26:29], v[174:177], v[190:193], v[26:29]
	v_mfma_f32_16x16x32_bf16 v[18:21], v[156:159], v[210:213], v[18:21]
	v_mfma_f32_16x16x32_bf16 v[10:13], v[174:177], v[210:213], v[10:13]
	v_mfma_f32_16x16x32_bf16 v[6:9], v[156:159], v[218:221], v[6:9]
	v_mfma_f32_16x16x32_bf16 v[2:5], v[174:177], v[218:221], v[2:5]
	v_mfma_f32_16x16x32_bf16 v[50:53], v[170:173], v[186:189], v[50:53]
	v_mfma_f32_16x16x32_bf16 v[42:45], v[178:181], v[186:189], v[42:45]
	v_mfma_f32_16x16x32_bf16 v[34:37], v[170:173], v[204:207], v[34:37]
	v_mfma_f32_16x16x32_bf16 v[26:29], v[178:181], v[204:207], v[26:29]
	v_mfma_f32_16x16x32_bf16 v[18:21], v[170:173], v[214:217], v[18:21]
	v_mfma_f32_16x16x32_bf16 v[10:13], v[178:181], v[214:217], v[10:13]
	v_mfma_f32_16x16x32_bf16 v[6:9], v[170:173], v[222:225], v[6:9]
	v_mfma_f32_16x16x32_bf16 v[2:5], v[178:181], v[222:225], v[2:5]
	s_barrier
; #define PG8_STAGE(bufoff, gbase, voff) do { _Pragma("unroll") for (int _i = 0; _i < 2; ++_i) \
;         __builtin_amdgcn_global_load_lds((const gunsigned*)((const gchar*)(gbase) + (voff)[_i]), (LAS unsigned*)(lds + (bufoff) + ldsw + _i * 8192), 16, 0, 0); } while (0)
; #define PG8_LDA(dst, b, h) do { _Pragma("unroll") for (int m = 0; m < 4; ++m) _Pragma("unroll") for (int k = 0; k < 2; ++k) dst[m][k] = *(const LAS bf16x8*)(lds + PG8_SA(b, h) + aoff + m * 2048 + k * 1024); } while (0)
; #define PG8_LDB(dst, b, h) do { _Pragma("unroll") for (int n = 0; n < 2; ++n) _Pragma("unroll") for (int k = 0; k < 2; ++k) dst[n][k] = *(const LAS bf16x8*)(lds + PG8_SB(b, h) + boff + n * 2048 + k * 1024); } while (0)
; #define PG8_MMA(ai, bj, At, Bt) do { __builtin_amdgcn_s_setprio(1); _Pragma("unroll") for (int m = 0; m < 4; ++m) _Pragma("unroll") for (int n = 0; n < 2; ++n) _Pragma("unroll") for (int k = 0; k < 2; ++k) \
;         acc[ai][bj][m][n] = __builtin_amdgcn_mfma_f32_16x16x32_bf16(Bt[n][k], At[m][k], acc[ai][bj][m][n], 0, 0, 0); __builtin_amdgcn_s_setprio(0); } while (0)
; #define PG8_WAIT_V(n) asm volatile("s_waitcnt vmcnt(" #n ")" ::: "memory")
; #define PG8_WAIT_L(n) asm volatile("s_waitcnt lgkmcnt(" #n ")" ::: "memory")
; #define PG8_BAR __builtin_amdgcn_s_barrier()
; #define PG8_SCHED __builtin_amdgcn_sched_barrier(0)
; template <class Epi, class Sched>
; __device__ __forceinline__ void gemm_phase(LAS unsigned char* lds, const int tid, const Gemm g, const Sched& S, const Epi& E) {
;     ...
;             PG8_LDB(B0, 1, 0); PG8_LDB(B1, 1, 1); PG8_SCHED; PG8_LDA(At, 1, 0); PG8_STAGE(PG8_SA(0, 1), a2 + hstep, voffA);
;             PG8_WAIT_V(8); PG8_WAIT_L(0); PG8_BAR; PG8_MMA(0, 0, At, B0); PG8_MMA(0, 1, At, B1); PG8_BAR; PG8_SCHED;
;             PG8_LDA(At, 1, 1); PG8_STAGE(PG8_SB(1, 0), b3, voffB); PG8_STAGE(PG8_SB(1, 1), b3 + hstep, voffB); PG8_STAGE(PG8_SA(1, 0), a3, voffA);
;             PG8_WAIT_V(8); PG8_WAIT_L(0); PG8_BAR; PG8_MMA(1, 0, At, B0); PG8_MMA(1, 1, At, B1); PG8_BAR; PG8_SCHED;
;         }
;         if (wr == 0) PG8_BAR;
	s_setprio 0
	s_add_i32 s29, 0, 0x18000
	s_add_i32 s30, 0, 0x1c000
	s_add_u32 s48, s62, 0x40000
	s_addc_u32 s49, s63, 0
	s_mov_b32 m0, s36
	global_load_lds_dwordx4 v138, s[48:49]
	s_mov_b32 m0, s37
	s_nop 0
	global_load_lds_dwordx4 v136, s[48:49]
	v_add_u32_e32 v152, s29, v165
	v_add_u32_e32 v162, s30, v165
	ds_read_b128 v[130:133], v152
	ds_read_b128 v[144:147], v152 offset:1024
	ds_read_b128 v[148:151], v152 offset:2048
	ds_read_b128 v[152:155], v152 offset:3072
	ds_read_b128 v[156:159], v162
	ds_read_b128 v[170:173], v162 offset:1024
	ds_read_b128 v[174:177], v162 offset:2048
	ds_read_b128 v[178:181], v162 offset:3072
	ds_read_b128 v[182:185], v169 offset:32768
	ds_read_b128 v[186:189], v169 offset:33792
	ds_read_b128 v[190:193], v169 offset:34816
	ds_read_b128 v[204:207], v169 offset:35840
	ds_read_b128 v[210:213], v169 offset:36864
	ds_read_b128 v[214:217], v169 offset:37888
	ds_read_b128 v[218:221], v169 offset:38912
	ds_read_b128 v[222:225], v169 offset:39936
	s_waitcnt vmcnt(8)
	s_waitcnt lgkmcnt(0)
	s_setprio 1
	s_barrier
	v_mfma_f32_16x16x32_bf16 v[126:129], v[130:133], v[182:185], v[126:129]
	v_mfma_f32_16x16x32_bf16 v[122:125], v[148:151], v[182:185], v[122:125]
	v_mfma_f32_16x16x32_bf16 v[118:121], v[130:133], v[190:193], v[118:121]
	v_mfma_f32_16x16x32_bf16 v[110:113], v[148:151], v[190:193], v[110:113]
	v_mfma_f32_16x16x32_bf16 v[102:105], v[130:133], v[210:213], v[102:105]
	v_mfma_f32_16x16x32_bf16 v[94:97], v[148:151], v[210:213], v[94:97]
	v_mfma_f32_16x16x32_bf16 v[86:89], v[130:133], v[218:221], v[86:89]
	v_mfma_f32_16x16x32_bf16 v[78:81], v[148:151], v[218:221], v[78:81]
	v_mfma_f32_16x16x32_bf16 v[126:129], v[144:147], v[186:189], v[126:129]
	v_mfma_f32_16x16x32_bf16 v[122:125], v[152:155], v[186:189], v[122:125]
	v_mfma_f32_16x16x32_bf16 v[118:121], v[144:147], v[204:207], v[118:121]
	v_mfma_f32_16x16x32_bf16 v[110:113], v[152:155], v[204:207], v[110:113]
	v_mfma_f32_16x16x32_bf16 v[102:105], v[144:147], v[214:217], v[102:105]
	v_mfma_f32_16x16x32_bf16 v[94:97], v[152:155], v[214:217], v[94:97]
	v_mfma_f32_16x16x32_bf16 v[86:89], v[144:147], v[222:225], v[86:89]
	v_mfma_f32_16x16x32_bf16 v[78:81], v[152:155], v[222:225], v[78:81]
	s_setprio 0
	s_setprio 1
	v_mfma_f32_16x16x32_bf16 v[114:117], v[156:159], v[182:185], v[114:117]
	v_mfma_f32_16x16x32_bf16 v[106:109], v[174:177], v[182:185], v[106:109]
	v_mfma_f32_16x16x32_bf16 v[98:101], v[156:159], v[190:193], v[98:101]
	v_mfma_f32_16x16x32_bf16 v[90:93], v[174:177], v[190:193], v[90:93]
	v_mfma_f32_16x16x32_bf16 v[82:85], v[156:159], v[210:213], v[82:85]
	v_mfma_f32_16x16x32_bf16 v[74:77], v[174:177], v[210:213], v[74:77]
	v_mfma_f32_16x16x32_bf16 v[70:73], v[156:159], v[218:221], v[70:73]
	v_mfma_f32_16x16x32_bf16 v[66:69], v[174:177], v[218:221], v[66:69]
	v_mfma_f32_16x16x32_bf16 v[114:117], v[170:173], v[186:189], v[114:117]
	v_mfma_f32_16x16x32_bf16 v[106:109], v[178:181], v[186:189], v[106:109]
	v_mfma_f32_16x16x32_bf16 v[98:101], v[170:173], v[204:207], v[98:101]
	v_mfma_f32_16x16x32_bf16 v[90:93], v[178:181], v[204:207], v[90:93]
	v_mfma_f32_16x16x32_bf16 v[82:85], v[170:173], v[214:217], v[82:85]
	v_mfma_f32_16x16x32_bf16 v[74:77], v[178:181], v[214:217], v[74:77]
	v_mfma_f32_16x16x32_bf16 v[70:73], v[170:173], v[222:225], v[70:73]
	v_mfma_f32_16x16x32_bf16 v[66:69], v[178:181], v[222:225], v[66:69]
	s_barrier
	s_setprio 0
	s_add_i32 s29, s29, s12
	s_mov_b32 m0, s29
	ds_read_b128 v[182:185], v169 offset:49152
	global_load_lds_dwordx4 v161, s[20:21]
	s_add_i32 m0, s29, 0x2000
	s_add_i32 s29, s30, s12
	global_load_lds_dwordx4 v195, s[20:21]
	s_add_u32 s20, s20, 0x40080
	s_addc_u32 s21, s21, 0
	s_mov_b32 m0, s29
	s_nop 0
	global_load_lds_dwordx4 v0, s[20:21]
	s_add_i32 m0, s29, 0x2000
	s_nop 0
	global_load_lds_dwordx4 v134, s[20:21]
	s_mov_b32 m0, s38
	s_nop 0
	global_load_lds_dwordx4 v201, s[62:63]
	s_mov_b32 m0, s39
	s_nop 0
	global_load_lds_dwordx4 v227, s[62:63]
	ds_read_b128 v[186:189], v169 offset:50176
	ds_read_b128 v[190:193], v169 offset:51200
	ds_read_b128 v[204:207], v169 offset:52224
	ds_read_b128 v[210:213], v169 offset:53248
	ds_read_b128 v[214:217], v169 offset:54272
	ds_read_b128 v[218:221], v169 offset:55296
	ds_read_b128 v[222:225], v169 offset:56320
	s_waitcnt vmcnt(8)
	s_waitcnt lgkmcnt(0)
	s_setprio 1
	s_barrier
	v_mfma_f32_16x16x32_bf16 v[62:65], v[130:133], v[182:185], v[62:65]
	v_mfma_f32_16x16x32_bf16 v[58:61], v[148:151], v[182:185], v[58:61]
	v_mfma_f32_16x16x32_bf16 v[54:57], v[130:133], v[190:193], v[54:57]
	v_mfma_f32_16x16x32_bf16 v[46:49], v[148:151], v[190:193], v[46:49]
	v_mfma_f32_16x16x32_bf16 v[38:41], v[130:133], v[210:213], v[38:41]
	v_mfma_f32_16x16x32_bf16 v[30:33], v[148:151], v[210:213], v[30:33]
	v_mfma_f32_16x16x32_bf16 v[22:25], v[130:133], v[218:221], v[22:25]
	v_mfma_f32_16x16x32_bf16 v[14:17], v[148:151], v[218:221], v[14:17]
	v_mfma_f32_16x16x32_bf16 v[62:65], v[144:147], v[186:189], v[62:65]
	v_mfma_f32_16x16x32_bf16 v[58:61], v[152:155], v[186:189], v[58:61]
	v_mfma_f32_16x16x32_bf16 v[54:57], v[144:147], v[204:207], v[54:57]
	v_mfma_f32_16x16x32_bf16 v[46:49], v[152:155], v[204:207], v[46:49]
	v_mfma_f32_16x16x32_bf16 v[38:41], v[144:147], v[214:217], v[38:41]
	v_mfma_f32_16x16x32_bf16 v[30:33], v[152:155], v[214:217], v[30:33]
	v_mfma_f32_16x16x32_bf16 v[22:25], v[144:147], v[222:225], v[22:25]
	v_mfma_f32_16x16x32_bf16 v[14:17], v[152:155], v[222:225], v[14:17]
	s_setprio 0
	s_setprio 1
	v_mfma_f32_16x16x32_bf16 v[50:53], v[156:159], v[182:185], v[50:53]
	v_mfma_f32_16x16x32_bf16 v[42:45], v[174:177], v[182:185], v[42:45]
	v_mfma_f32_16x16x32_bf16 v[34:37], v[156:159], v[190:193], v[34:37]
	v_mfma_f32_16x16x32_bf16 v[26:29], v[174:177], v[190:193], v[26:29]
	v_mfma_f32_16x16x32_bf16 v[18:21], v[156:159], v[210:213], v[18:21]
	v_mfma_f32_16x16x32_bf16 v[10:13], v[174:177], v[210:213], v[10:13]
	v_mfma_f32_16x16x32_bf16 v[6:9], v[156:159], v[218:221], v[6:9]
	v_mfma_f32_16x16x32_bf16 v[2:5], v[174:177], v[218:221], v[2:5]
	v_mfma_f32_16x16x32_bf16 v[50:53], v[170:173], v[186:189], v[50:53]
	v_mfma_f32_16x16x32_bf16 v[42:45], v[178:181], v[186:189], v[42:45]
	v_mfma_f32_16x16x32_bf16 v[34:37], v[170:173], v[204:207], v[34:37]
	v_mfma_f32_16x16x32_bf16 v[26:29], v[178:181], v[204:207], v[26:29]
	v_mfma_f32_16x16x32_bf16 v[18:21], v[170:173], v[214:217], v[18:21]
	v_mfma_f32_16x16x32_bf16 v[10:13], v[178:181], v[214:217], v[10:13]
	v_mfma_f32_16x16x32_bf16 v[6:9], v[170:173], v[222:225], v[6:9]
	v_mfma_f32_16x16x32_bf16 v[2:5], v[178:181], v[222:225], v[2:5]
	s_barrier
	s_setprio 0
	s_add_i32 s46, s46, 2
	s_add_u32 s44, s44, 0x100
	s_addc_u32 s45, s45, 0
	s_add_u32 s60, s60, 0x100
	s_addc_u32 s61, s61, 0
	s_cmp_gt_u32 s46, 13
	s_cbranch_scc0 .LBB0_559
	s_and_b64 vcc, exec, s[4:5]
	s_cbranch_vccz .LBB0_562
	s_barrier

; #define PG8_STAGE(bufoff, gbase, voff) do { _Pragma("unroll") for (int _i = 0; _i < 2; ++_i) \
;         __builtin_amdgcn_global_load_lds((const gunsigned*)((const gchar*)(gbase) + (voff)[_i]), (LAS unsigned*)(lds + (bufoff) + ldsw + _i * 8192), 16, 0, 0); } while (0)
; #define PG8_LDA(dst, b, h) do { _Pragma("unroll") for (int m = 0; m < 4; ++m) _Pragma("unroll") for (int k = 0; k < 2; ++k) dst[m][k] = *(const LAS bf16x8*)(lds + PG8_SA(b, h) + aoff + m * 2048 + k * 1024); } while (0)
; #define PG8_LDB(dst, b, h) do { _Pragma("unroll") for (int n = 0; n < 2; ++n) _Pragma("unroll") for (int k = 0; k < 2; ++k) dst[n][k] = *(const LAS bf16x8*)(lds + PG8_SB(b, h) + boff + n * 2048 + k * 1024); } while (0)
; #define PG8_MMA(ai, bj, At, Bt) do { __builtin_amdgcn_s_setprio(1); _Pragma("unroll") for (int m = 0; m < 4; ++m) _Pragma("unroll") for (int n = 0; n < 2; ++n) _Pragma("unroll") for (int k = 0; k < 2; ++k) \
;         acc[ai][bj][m][n] = __builtin_amdgcn_mfma_f32_16x16x32_bf16(Bt[n][k], At[m][k], acc[ai][bj][m][n], 0, 0, 0); __builtin_amdgcn_s_setprio(0); } while (0)
; #define PG8_WAIT_V(n) asm volatile("s_waitcnt vmcnt(" #n ")" ::: "memory")
; #define PG8_WAIT_L(n) asm volatile("s_waitcnt lgkmcnt(" #n ")" ::: "memory")
; #define PG8_BAR __builtin_amdgcn_s_barrier()
; #define PG8_SCHED __builtin_amdgcn_sched_barrier(0)
; template <class Epi, class Sched>
; __device__ __forceinline__ void gemm_phase(LAS unsigned char* lds, const int tid, const Gemm g, const Sched& S, const Epi& E) {
;     ...
;             const gchar* a1 = cA + (size_t)(t + 1) * kstep;
;             const gchar* a2 = last ? nA : cA + (size_t)(t + 2) * kstep; const gchar* b2 = last ? nB : cB + (size_t)(t + 2) * kstep;
;             const gchar* a3 = a2 + kstep; const gchar* b3 = b2 + kstep;
;             PG8_LDB(B0, 0, 0); PG8_LDB(B1, 0, 1); PG8_SCHED; PG8_LDA(At, 0, 0); PG8_STAGE(PG8_SA(1, 1), a1 + hstep, voffA);
;             PG8_WAIT_V(8); PG8_WAIT_L(0); PG8_BAR; PG8_MMA(0, 0, At, B0); PG8_MMA(0, 1, At, B1); PG8_BAR; PG8_SCHED;
;             PG8_LDA(At, 0, 1); PG8_STAGE(PG8_SB(0, 0), b2, voffB); PG8_STAGE(PG8_SB(0, 1), b2 + hstep, voffB); PG8_STAGE(PG8_SA(0, 0), a2, voffA);
;             PG8_WAIT_V(8); PG8_WAIT_L(0); PG8_BAR; PG8_MMA(1, 0, At, B0); PG8_MMA(1, 1, At, B1); PG8_BAR; PG8_SCHED;
.LBB0_598:
	s_add_u32 s20, s62, 0x100
	s_addc_u32 s21, s63, 0
	s_add_i32 s29, 0, 0x10000
	s_cmp_eq_u32 s45, 40
	s_cselect_b32 s73, s9, s21
	s_cselect_b32 s72, s8, s20
	s_cselect_b32 s67, s61, s44
	s_cselect_b32 s66, s60, s31
	s_add_i32 s48, 0, 0x14000
	s_add_i32 m0, s34, 0xc000
	global_load_lds_dwordx4 v186, s[62:63]
	s_add_i32 m0, s34, 0xe000
	s_nop 0
	global_load_lds_dwordx4 v184, s[62:63]
	v_add_u32_e32 v142, s29, v210
	v_add_u32_e32 v158, s48, v210
	ds_read_b128 v[130:133], v142
	ds_read_b128 v[134:137], v142 offset:1024
	ds_read_b128 v[138:141], v142 offset:2048
	ds_read_b128 v[142:145], v142 offset:3072
	ds_read_b128 v[146:149], v158
	ds_read_b128 v[150:153], v158 offset:1024
	ds_read_b128 v[154:157], v158 offset:2048
	ds_read_b128 v[158:161], v158 offset:3072
	ds_read_b128 v[162:165], v214
	ds_read_b128 v[166:169], v214 offset:1024
	ds_read_b128 v[170:173], v214 offset:2048
	ds_read_b128 v[174:177], v214 offset:3072
	ds_read_b128 v[188:191], v214 offset:4096
	ds_read_b128 v[192:195], v214 offset:5120
	ds_read_b128 v[204:207], v214 offset:6144
	ds_read_b128 v[216:219], v214 offset:7168
	s_waitcnt vmcnt(8)
	s_waitcnt lgkmcnt(0)
	s_setprio 1
	s_barrier
	v_mfma_f32_16x16x32_bf16 v[126:129], v[130:133], v[162:165], v[126:129]
	v_mfma_f32_16x16x32_bf16 v[122:125], v[138:141], v[162:165], v[122:125]
	v_mfma_f32_16x16x32_bf16 v[110:113], v[130:133], v[170:173], v[110:113]
	v_mfma_f32_16x16x32_bf16 v[106:109], v[138:141], v[170:173], v[106:109]
	v_mfma_f32_16x16x32_bf16 v[94:97], v[130:133], v[188:191], v[94:97]
	v_mfma_f32_16x16x32_bf16 v[90:93], v[138:141], v[188:191], v[90:93]
	v_mfma_f32_16x16x32_bf16 v[78:81], v[130:133], v[204:207], v[78:81]
	v_mfma_f32_16x16x32_bf16 v[74:77], v[138:141], v[204:207], v[74:77]
	v_mfma_f32_16x16x32_bf16 v[126:129], v[134:137], v[166:169], v[126:129]
	v_mfma_f32_16x16x32_bf16 v[122:125], v[142:145], v[166:169], v[122:125]
	v_mfma_f32_16x16x32_bf16 v[110:113], v[134:137], v[174:177], v[110:113]
	v_mfma_f32_16x16x32_bf16 v[106:109], v[142:145], v[174:177], v[106:109]
	v_mfma_f32_16x16x32_bf16 v[94:97], v[134:137], v[192:195], v[94:97]
	v_mfma_f32_16x16x32_bf16 v[90:93], v[142:145], v[192:195], v[90:93]
	v_mfma_f32_16x16x32_bf16 v[78:81], v[134:137], v[216:219], v[78:81]
	v_mfma_f32_16x16x32_bf16 v[74:77], v[142:145], v[216:219], v[74:77]
	s_setprio 0
	s_setprio 1
	v_mfma_f32_16x16x32_bf16 v[118:121], v[146:149], v[162:165], v[118:121]
	v_mfma_f32_16x16x32_bf16 v[114:117], v[154:157], v[162:165], v[114:117]
	v_mfma_f32_16x16x32_bf16 v[102:105], v[146:149], v[170:173], v[102:105]
	v_mfma_f32_16x16x32_bf16 v[98:101], v[154:157], v[170:173], v[98:101]
	v_mfma_f32_16x16x32_bf16 v[86:89], v[146:149], v[188:191], v[86:89]
	v_mfma_f32_16x16x32_bf16 v[82:85], v[154:157], v[188:191], v[82:85]
	v_mfma_f32_16x16x32_bf16 v[70:73], v[146:149], v[204:207], v[70:73]
	v_mfma_f32_16x16x32_bf16 v[66:69], v[154:157], v[204:207], v[66:69]
	v_mfma_f32_16x16x32_bf16 v[118:121], v[150:153], v[166:169], v[118:121]
	v_mfma_f32_16x16x32_bf16 v[114:117], v[158:161], v[166:169], v[114:117]
	v_mfma_f32_16x16x32_bf16 v[102:105], v[150:153], v[174:177], v[102:105]
	v_mfma_f32_16x16x32_bf16 v[98:101], v[158:161], v[174:177], v[98:101]
	v_mfma_f32_16x16x32_bf16 v[86:89], v[150:153], v[192:195], v[86:89]
	v_mfma_f32_16x16x32_bf16 v[82:85], v[158:161], v[192:195], v[82:85]
	v_mfma_f32_16x16x32_bf16 v[70:73], v[150:153], v[216:219], v[70:73]
	v_mfma_f32_16x16x32_bf16 v[66:69], v[158:161], v[216:219], v[66:69]
	s_barrier
	s_setprio 0
	s_add_i32 s29, s29, s15
	s_mov_b32 m0, s29
	global_load_lds_dwordx4 v0, s[66:67]
	s_add_i32 m0, s29, 0x2000
	s_add_u32 s46, s66, 0xb0000
	s_addc_u32 s47, s67, 0
	s_add_i32 s29, s48, s15
	global_load_lds_dwordx4 v182, s[66:67]
	s_mov_b32 m0, s29
	s_nop 0
	global_load_lds_dwordx4 v0, s[46:47]
	s_add_i32 m0, s29, 0x2000
	s_nop 0
	global_load_lds_dwordx4 v182, s[46:47]
	s_mov_b32 m0, s34
	s_nop 0
	global_load_lds_dwordx4 v178, s[72:73]
	s_mov_b32 m0, s12
	s_nop 0
	global_load_lds_dwordx4 v180, s[72:73]
	ds_read_b128 v[162:165], v214 offset:16384
	ds_read_b128 v[166:169], v214 offset:17408
	ds_read_b128 v[170:173], v214 offset:18432
	ds_read_b128 v[174:177], v214 offset:19456
	ds_read_b128 v[188:191], v214 offset:20480
	ds_read_b128 v[192:195], v214 offset:21504
	ds_read_b128 v[204:207], v214 offset:22528
	ds_read_b128 v[216:219], v214 offset:23552
	s_waitcnt vmcnt(8)
	s_waitcnt lgkmcnt(0)
	s_setprio 1
	s_barrier
	v_mfma_f32_16x16x32_bf16 v[62:65], v[130:133], v[162:165], v[62:65]
	v_mfma_f32_16x16x32_bf16 v[58:61], v[138:141], v[162:165], v[58:61]
	v_mfma_f32_16x16x32_bf16 v[46:49], v[130:133], v[170:173], v[46:49]
	v_mfma_f32_16x16x32_bf16 v[42:45], v[138:141], v[170:173], v[42:45]
	v_mfma_f32_16x16x32_bf16 v[30:33], v[130:133], v[188:191], v[30:33]
	v_mfma_f32_16x16x32_bf16 v[26:29], v[138:141], v[188:191], v[26:29]
	v_mfma_f32_16x16x32_bf16 v[14:17], v[130:133], v[204:207], v[14:17]
	v_mfma_f32_16x16x32_bf16 v[10:13], v[138:141], v[204:207], v[10:13]
	v_mfma_f32_16x16x32_bf16 v[62:65], v[134:137], v[166:169], v[62:65]
	v_mfma_f32_16x16x32_bf16 v[58:61], v[142:145], v[166:169], v[58:61]
	v_mfma_f32_16x16x32_bf16 v[46:49], v[134:137], v[174:177], v[46:49]
	v_mfma_f32_16x16x32_bf16 v[42:45], v[142:145], v[174:177], v[42:45]
	v_mfma_f32_16x16x32_bf16 v[30:33], v[134:137], v[192:195], v[30:33]
	v_mfma_f32_16x16x32_bf16 v[26:29], v[142:145], v[192:195], v[26:29]
	v_mfma_f32_16x16x32_bf16 v[14:17], v[134:137], v[216:219], v[14:17]
	v_mfma_f32_16x16x32_bf16 v[10:13], v[142:145], v[216:219], v[10:13]
	s_setprio 0
	s_setprio 1
	v_mfma_f32_16x16x32_bf16 v[54:57], v[146:149], v[162:165], v[54:57]
	v_mfma_f32_16x16x32_bf16 v[50:53], v[154:157], v[162:165], v[50:53]
	v_mfma_f32_16x16x32_bf16 v[38:41], v[146:149], v[170:173], v[38:41]
	v_mfma_f32_16x16x32_bf16 v[34:37], v[154:157], v[170:173], v[34:37]
	v_mfma_f32_16x16x32_bf16 v[22:25], v[146:149], v[188:191], v[22:25]
	v_mfma_f32_16x16x32_bf16 v[18:21], v[154:157], v[188:191], v[18:21]
	v_mfma_f32_16x16x32_bf16 v[6:9], v[146:149], v[204:207], v[6:9]
	v_mfma_f32_16x16x32_bf16 v[2:5], v[154:157], v[204:207], v[2:5]
	v_mfma_f32_16x16x32_bf16 v[54:57], v[150:153], v[166:169], v[54:57]
	v_mfma_f32_16x16x32_bf16 v[50:53], v[158:161], v[166:169], v[50:53]
	v_mfma_f32_16x16x32_bf16 v[38:41], v[150:153], v[174:177], v[38:41]
	v_mfma_f32_16x16x32_bf16 v[34:37], v[158:161], v[174:177], v[34:37]
	v_mfma_f32_16x16x32_bf16 v[22:25], v[150:153], v[192:195], v[22:25]
	v_mfma_f32_16x16x32_bf16 v[18:21], v[158:161], v[192:195], v[18:21]
	v_mfma_f32_16x16x32_bf16 v[6:9], v[150:153], v[216:219], v[6:9]
	v_mfma_f32_16x16x32_bf16 v[2:5], v[158:161], v[216:219], v[2:5]
	s_barrier
; #define PG8_STAGE(bufoff, gbase, voff) do { _Pragma("unroll") for (int _i = 0; _i < 2; ++_i) \
;         __builtin_amdgcn_global_load_lds((const gunsigned*)((const gchar*)(gbase) + (voff)[_i]), (LAS unsigned*)(lds + (bufoff) + ldsw + _i * 8192), 16, 0, 0); } while (0)
; #define PG8_LDA(dst, b, h) do { _Pragma("unroll") for (int m = 0; m < 4; ++m) _Pragma("unroll") for (int k = 0; k < 2; ++k) dst[m][k] = *(const LAS bf16x8*)(lds + PG8_SA(b, h) + aoff + m * 2048 + k * 1024); } while (0)
; #define PG8_LDB(dst, b, h) do { _Pragma("unroll") for (int n = 0; n < 2; ++n) _Pragma("unroll") for (int k = 0; k < 2; ++k) dst[n][k] = *(const LAS bf16x8*)(lds + PG8_SB(b, h) + boff + n * 2048 + k * 1024); } while (0)
; #define PG8_MMA(ai, bj, At, Bt) do { __builtin_amdgcn_s_setprio(1); _Pragma("unroll") for (int m = 0; m < 4; ++m) _Pragma("unroll") for (int n = 0; n < 2; ++n) _Pragma("unroll") for (int k = 0; k < 2; ++k) \
;         acc[ai][bj][m][n] = __builtin_amdgcn_mfma_f32_16x16x32_bf16(Bt[n][k], At[m][k], acc[ai][bj][m][n], 0, 0, 0); __builtin_amdgcn_s_setprio(0); } while (0)
; #define PG8_WAIT_V(n) asm volatile("s_waitcnt vmcnt(" #n ")" ::: "memory")
; #define PG8_WAIT_L(n) asm volatile("s_waitcnt lgkmcnt(" #n ")" ::: "memory")
; #define PG8_BAR __builtin_amdgcn_s_barrier()
; #define PG8_SCHED __builtin_amdgcn_sched_barrier(0)
; template <class Epi, class Sched>
; __device__ __forceinline__ void gemm_phase(LAS unsigned char* lds, const int tid, const Gemm g, const Sched& S, const Epi& E) {
;     ...
;             PG8_LDB(B0, 1, 0); PG8_LDB(B1, 1, 1); PG8_SCHED; PG8_LDA(At, 1, 0); PG8_STAGE(PG8_SA(0, 1), a2 + hstep, voffA);
;             PG8_WAIT_V(8); PG8_WAIT_L(0); PG8_BAR; PG8_MMA(0, 0, At, B0); PG8_MMA(0, 1, At, B1); PG8_BAR; PG8_SCHED;
;             PG8_LDA(At, 1, 1); PG8_STAGE(PG8_SB(1, 0), b3, voffB); PG8_STAGE(PG8_SB(1, 1), b3 + hstep, voffB); PG8_STAGE(PG8_SA(1, 0), a3, voffA);
;             PG8_WAIT_V(8); PG8_WAIT_L(0); PG8_BAR; PG8_MMA(1, 0, At, B0); PG8_MMA(1, 1, At, B1); PG8_BAR; PG8_SCHED;
;         }
;         if (wr == 0) PG8_BAR;
	s_setprio 0
	s_add_i32 s29, 0, 0x18000
	s_add_i32 s48, 0, 0x1c000
	s_add_u32 s46, s72, 0xb0000
	s_addc_u32 s47, s73, 0
	s_mov_b32 m0, s35
	global_load_lds_dwordx4 v178, s[46:47]
	s_mov_b32 m0, s36
	s_nop 0
	global_load_lds_dwordx4 v180, s[46:47]
	v_add_u32_e32 v142, s29, v210
	v_add_u32_e32 v158, s48, v210
	ds_read_b128 v[130:133], v142
	ds_read_b128 v[134:137], v142 offset:1024
	ds_read_b128 v[138:141], v142 offset:2048
	ds_read_b128 v[142:145], v142 offset:3072
	ds_read_b128 v[146:149], v158
	ds_read_b128 v[150:153], v158 offset:1024
	ds_read_b128 v[154:157], v158 offset:2048
	ds_read_b128 v[158:161], v158 offset:3072
	ds_read_b128 v[162:165], v214 offset:32768
	ds_read_b128 v[166:169], v214 offset:33792
	ds_read_b128 v[170:173], v214 offset:34816
	ds_read_b128 v[174:177], v214 offset:35840
	ds_read_b128 v[188:191], v214 offset:36864
	ds_read_b128 v[192:195], v214 offset:37888
	ds_read_b128 v[204:207], v214 offset:38912
	ds_read_b128 v[216:219], v214 offset:39936
	s_waitcnt vmcnt(8)
	s_waitcnt lgkmcnt(0)
	s_setprio 1
	s_barrier
	v_mfma_f32_16x16x32_bf16 v[126:129], v[130:133], v[162:165], v[126:129]
	v_mfma_f32_16x16x32_bf16 v[122:125], v[138:141], v[162:165], v[122:125]
	v_mfma_f32_16x16x32_bf16 v[110:113], v[130:133], v[170:173], v[110:113]
	v_mfma_f32_16x16x32_bf16 v[106:109], v[138:141], v[170:173], v[106:109]
	v_mfma_f32_16x16x32_bf16 v[94:97], v[130:133], v[188:191], v[94:97]
	v_mfma_f32_16x16x32_bf16 v[90:93], v[138:141], v[188:191], v[90:93]
	v_mfma_f32_16x16x32_bf16 v[78:81], v[130:133], v[204:207], v[78:81]
	v_mfma_f32_16x16x32_bf16 v[74:77], v[138:141], v[204:207], v[74:77]
	v_mfma_f32_16x16x32_bf16 v[126:129], v[134:137], v[166:169], v[126:129]
	v_mfma_f32_16x16x32_bf16 v[122:125], v[142:145], v[166:169], v[122:125]
	v_mfma_f32_16x16x32_bf16 v[110:113], v[134:137], v[174:177], v[110:113]
	v_mfma_f32_16x16x32_bf16 v[106:109], v[142:145], v[174:177], v[106:109]
	v_mfma_f32_16x16x32_bf16 v[94:97], v[134:137], v[192:195], v[94:97]
	v_mfma_f32_16x16x32_bf16 v[90:93], v[142:145], v[192:195], v[90:93]
	v_mfma_f32_16x16x32_bf16 v[78:81], v[134:137], v[216:219], v[78:81]
	v_mfma_f32_16x16x32_bf16 v[74:77], v[142:145], v[216:219], v[74:77]
	s_setprio 0
	s_setprio 1
	v_mfma_f32_16x16x32_bf16 v[118:121], v[146:149], v[162:165], v[118:121]
	v_mfma_f32_16x16x32_bf16 v[114:117], v[154:157], v[162:165], v[114:117]
	v_mfma_f32_16x16x32_bf16 v[102:105], v[146:149], v[170:173], v[102:105]
	v_mfma_f32_16x16x32_bf16 v[98:101], v[154:157], v[170:173], v[98:101]
	v_mfma_f32_16x16x32_bf16 v[86:89], v[146:149], v[188:191], v[86:89]
	v_mfma_f32_16x16x32_bf16 v[82:85], v[154:157], v[188:191], v[82:85]
	v_mfma_f32_16x16x32_bf16 v[70:73], v[146:149], v[204:207], v[70:73]
	v_mfma_f32_16x16x32_bf16 v[66:69], v[154:157], v[204:207], v[66:69]
	v_mfma_f32_16x16x32_bf16 v[118:121], v[150:153], v[166:169], v[118:121]
	v_mfma_f32_16x16x32_bf16 v[114:117], v[158:161], v[166:169], v[114:117]
	v_mfma_f32_16x16x32_bf16 v[102:105], v[150:153], v[174:177], v[102:105]
	v_mfma_f32_16x16x32_bf16 v[98:101], v[158:161], v[174:177], v[98:101]
	v_mfma_f32_16x16x32_bf16 v[86:89], v[150:153], v[192:195], v[86:89]
	v_mfma_f32_16x16x32_bf16 v[82:85], v[158:161], v[192:195], v[82:85]
	v_mfma_f32_16x16x32_bf16 v[70:73], v[150:153], v[216:219], v[70:73]
	v_mfma_f32_16x16x32_bf16 v[66:69], v[158:161], v[216:219], v[66:69]
	s_barrier
	s_setprio 0
	s_add_i32 s29, s29, s15
	s_mov_b32 m0, s29
	ds_read_b128 v[162:165], v214 offset:49152
	global_load_lds_dwordx4 v221, s[66:67]
	s_add_i32 m0, s29, 0x2000
	s_add_u32 s46, s66, 0xb0080
	s_addc_u32 s47, s67, 0
	s_add_i32 s29, s48, s15
	global_load_lds_dwordx4 v223, s[66:67]
	s_mov_b32 m0, s29
	s_nop 0
	global_load_lds_dwordx4 v0, s[46:47]
	s_add_i32 m0, s29, 0x2000
	s_nop 0
	global_load_lds_dwordx4 v182, s[46:47]
	s_mov_b32 m0, s37
	s_nop 0
	global_load_lds_dwordx4 v225, s[72:73]
	s_mov_b32 m0, s38
	s_nop 0
	global_load_lds_dwordx4 v227, s[72:73]
	ds_read_b128 v[166:169], v214 offset:50176
	ds_read_b128 v[170:173], v214 offset:51200
	ds_read_b128 v[174:177], v214 offset:52224
	ds_read_b128 v[188:191], v214 offset:53248
	ds_read_b128 v[192:195], v214 offset:54272
	ds_read_b128 v[204:207], v214 offset:55296
	ds_read_b128 v[216:219], v214 offset:56320
	s_waitcnt vmcnt(8)
	s_waitcnt lgkmcnt(0)
	s_setprio 1
	s_barrier
	v_mfma_f32_16x16x32_bf16 v[62:65], v[130:133], v[162:165], v[62:65]
	v_mfma_f32_16x16x32_bf16 v[58:61], v[138:141], v[162:165], v[58:61]
	v_mfma_f32_16x16x32_bf16 v[46:49], v[130:133], v[170:173], v[46:49]
	v_mfma_f32_16x16x32_bf16 v[42:45], v[138:141], v[170:173], v[42:45]
	v_mfma_f32_16x16x32_bf16 v[30:33], v[130:133], v[188:191], v[30:33]
	v_mfma_f32_16x16x32_bf16 v[26:29], v[138:141], v[188:191], v[26:29]
	v_mfma_f32_16x16x32_bf16 v[14:17], v[130:133], v[204:207], v[14:17]
	v_mfma_f32_16x16x32_bf16 v[10:13], v[138:141], v[204:207], v[10:13]
	v_mfma_f32_16x16x32_bf16 v[62:65], v[134:137], v[166:169], v[62:65]
	v_mfma_f32_16x16x32_bf16 v[58:61], v[142:145], v[166:169], v[58:61]
	v_mfma_f32_16x16x32_bf16 v[46:49], v[134:137], v[174:177], v[46:49]
	v_mfma_f32_16x16x32_bf16 v[42:45], v[142:145], v[174:177], v[42:45]
	v_mfma_f32_16x16x32_bf16 v[30:33], v[134:137], v[192:195], v[30:33]
	v_mfma_f32_16x16x32_bf16 v[26:29], v[142:145], v[192:195], v[26:29]
	v_mfma_f32_16x16x32_bf16 v[14:17], v[134:137], v[216:219], v[14:17]
	v_mfma_f32_16x16x32_bf16 v[10:13], v[142:145], v[216:219], v[10:13]
	s_setprio 0
	s_setprio 1
	v_mfma_f32_16x16x32_bf16 v[54:57], v[146:149], v[162:165], v[54:57]
	v_mfma_f32_16x16x32_bf16 v[50:53], v[154:157], v[162:165], v[50:53]
	v_mfma_f32_16x16x32_bf16 v[38:41], v[146:149], v[170:173], v[38:41]
	v_mfma_f32_16x16x32_bf16 v[34:37], v[154:157], v[170:173], v[34:37]
	v_mfma_f32_16x16x32_bf16 v[22:25], v[146:149], v[188:191], v[22:25]
	v_mfma_f32_16x16x32_bf16 v[18:21], v[154:157], v[188:191], v[18:21]
	v_mfma_f32_16x16x32_bf16 v[6:9], v[146:149], v[204:207], v[6:9]
	v_mfma_f32_16x16x32_bf16 v[2:5], v[154:157], v[204:207], v[2:5]
	v_mfma_f32_16x16x32_bf16 v[54:57], v[150:153], v[166:169], v[54:57]
	v_mfma_f32_16x16x32_bf16 v[50:53], v[158:161], v[166:169], v[50:53]
	v_mfma_f32_16x16x32_bf16 v[38:41], v[150:153], v[174:177], v[38:41]
	v_mfma_f32_16x16x32_bf16 v[34:37], v[158:161], v[174:177], v[34:37]
	v_mfma_f32_16x16x32_bf16 v[22:25], v[150:153], v[192:195], v[22:25]
	v_mfma_f32_16x16x32_bf16 v[18:21], v[158:161], v[192:195], v[18:21]
	v_mfma_f32_16x16x32_bf16 v[6:9], v[150:153], v[216:219], v[6:9]
	v_mfma_f32_16x16x32_bf16 v[2:5], v[158:161], v[216:219], v[2:5]
	s_barrier
	s_setprio 0
	s_add_i32 s45, s45, 2
	s_add_u32 s31, s31, 0x100
	s_addc_u32 s44, s44, 0
	s_cmp_gt_u32 s45, 41
	s_mov_b64 s[62:63], s[20:21]
	s_cbranch_scc0 .LBB0_598
	s_and_b64 vcc, exec, s[58:59]
	s_cbranch_vccz .LBB0_601
	s_barrier

; #define PG8_STAGE(bufoff, gbase, voff) do { _Pragma("unroll") for (int _i = 0; _i < 2; ++_i) \
;         __builtin_amdgcn_global_load_lds((const gunsigned*)((const gchar*)(gbase) + (voff)[_i]), (LAS unsigned*)(lds + (bufoff) + ldsw + _i * 8192), 16, 0, 0); } while (0)
; #define PG8_LDA(dst, b, h) do { _Pragma("unroll") for (int m = 0; m < 4; ++m) _Pragma("unroll") for (int k = 0; k < 2; ++k) dst[m][k] = *(const LAS bf16x8*)(lds + PG8_SA(b, h) + aoff + m * 2048 + k * 1024); } while (0)
; #define PG8_LDB(dst, b, h) do { _Pragma("unroll") for (int n = 0; n < 2; ++n) _Pragma("unroll") for (int k = 0; k < 2; ++k) dst[n][k] = *(const LAS bf16x8*)(lds + PG8_SB(b, h) + boff + n * 2048 + k * 1024); } while (0)
; #define PG8_MMA(ai, bj, At, Bt) do { __builtin_amdgcn_s_setprio(1); _Pragma("unroll") for (int m = 0; m < 4; ++m) _Pragma("unroll") for (int n = 0; n < 2; ++n) _Pragma("unroll") for (int k = 0; k < 2; ++k) \
;         acc[ai][bj][m][n] = __builtin_amdgcn_mfma_f32_16x16x32_bf16(Bt[n][k], At[m][k], acc[ai][bj][m][n], 0, 0, 0); __builtin_amdgcn_s_setprio(0); } while (0)
; #define PG8_WAIT_V(n) asm volatile("s_waitcnt vmcnt(" #n ")" ::: "memory")
; #define PG8_WAIT_L(n) asm volatile("s_waitcnt lgkmcnt(" #n ")" ::: "memory")
; #define PG8_BAR __builtin_amdgcn_s_barrier()
; #define PG8_SCHED __builtin_amdgcn_sched_barrier(0)
; template <class Epi, class Sched>
; __device__ __forceinline__ void gemm_phase(LAS unsigned char* lds, const int tid, const Gemm g, const Sched& S, const Epi& E) {
;     ...
;             const gchar* a1 = cA + (size_t)(t + 1) * kstep;
;             const gchar* a2 = last ? nA : cA + (size_t)(t + 2) * kstep; const gchar* b2 = last ? nB : cB + (size_t)(t + 2) * kstep;
;             const gchar* a3 = a2 + kstep; const gchar* b3 = b2 + kstep;
;             PG8_LDB(B0, 0, 0); PG8_LDB(B1, 0, 1); PG8_SCHED; PG8_LDA(At, 0, 0); PG8_STAGE(PG8_SA(1, 1), a1 + hstep, voffA);
;             PG8_WAIT_V(8); PG8_WAIT_L(0); PG8_BAR; PG8_MMA(0, 0, At, B0); PG8_MMA(0, 1, At, B1); PG8_BAR; PG8_SCHED;
;             PG8_LDA(At, 0, 1); PG8_STAGE(PG8_SB(0, 0), b2, voffB); PG8_STAGE(PG8_SB(0, 1), b2 + hstep, voffB); PG8_STAGE(PG8_SA(0, 0), a2, voffA);
;             PG8_WAIT_V(8); PG8_WAIT_L(0); PG8_BAR; PG8_MMA(1, 0, At, B0); PG8_MMA(1, 1, At, B1); PG8_BAR; PG8_SCHED;
.LBB0_647:
	s_add_u32 s20, s58, 0xfffc0080
	s_addc_u32 s21, s59, -1
	s_add_i32 s42, 0, 0x10000
	s_cmp_eq_u32 s41, 12
	s_cselect_b32 s61, s9, s21
	s_cselect_b32 s60, s37, s20
	s_cselect_b32 s21, s7, s40
	s_cselect_b32 s20, s38, s39
	s_add_i32 s44, 0, 0x14000
	s_add_i32 m0, s23, 0xc000
	global_load_lds_dwordx4 v138, s[58:59]
	s_add_i32 m0, s23, 0xe000
	s_nop 0
	global_load_lds_dwordx4 v136, s[58:59]
	v_add_u32_e32 v140, s42, v143
	ds_read_b128 v[146:149], v140
	ds_read_b128 v[150:153], v140 offset:1024
	ds_read_b128 v[154:157], v140 offset:2048
	ds_read_b128 v[158:161], v140 offset:3072
	v_add_u32_e32 v140, s44, v143
	ds_read_b128 v[162:165], v140
	ds_read_b128 v[166:169], v140 offset:1024
	ds_read_b128 v[170:173], v140 offset:2048
	ds_read_b128 v[174:177], v140 offset:3072
	ds_read_b128 v[178:181], v145
	ds_read_b128 v[182:185], v145 offset:1024
	ds_read_b128 v[186:189], v145 offset:2048
	ds_read_b128 v[190:193], v145 offset:3072
	ds_read_b128 v[204:207], v145 offset:4096
	ds_read_b128 v[208:211], v145 offset:5120
	ds_read_b128 v[212:215], v145 offset:6144
	ds_read_b128 v[216:219], v145 offset:7168
	s_waitcnt vmcnt(8)
	s_waitcnt lgkmcnt(0)
	s_setprio 1
	s_barrier
	v_mfma_f32_16x16x32_bf16 v[126:129], v[146:149], v[178:181], v[126:129]
	v_mfma_f32_16x16x32_bf16 v[122:125], v[154:157], v[178:181], v[122:125]
	v_mfma_f32_16x16x32_bf16 v[110:113], v[146:149], v[186:189], v[110:113]
	v_mfma_f32_16x16x32_bf16 v[106:109], v[154:157], v[186:189], v[106:109]
	v_mfma_f32_16x16x32_bf16 v[94:97], v[146:149], v[204:207], v[94:97]
	v_mfma_f32_16x16x32_bf16 v[90:93], v[154:157], v[204:207], v[90:93]
	v_mfma_f32_16x16x32_bf16 v[78:81], v[146:149], v[212:215], v[78:81]
	v_mfma_f32_16x16x32_bf16 v[74:77], v[154:157], v[212:215], v[74:77]
	v_mfma_f32_16x16x32_bf16 v[126:129], v[150:153], v[182:185], v[126:129]
	v_mfma_f32_16x16x32_bf16 v[122:125], v[158:161], v[182:185], v[122:125]
	v_mfma_f32_16x16x32_bf16 v[110:113], v[150:153], v[190:193], v[110:113]
	v_mfma_f32_16x16x32_bf16 v[106:109], v[158:161], v[190:193], v[106:109]
	v_mfma_f32_16x16x32_bf16 v[94:97], v[150:153], v[208:211], v[94:97]
	v_mfma_f32_16x16x32_bf16 v[90:93], v[158:161], v[208:211], v[90:93]
	v_mfma_f32_16x16x32_bf16 v[78:81], v[150:153], v[216:219], v[78:81]
	v_mfma_f32_16x16x32_bf16 v[74:77], v[158:161], v[216:219], v[74:77]
	s_setprio 0
	s_setprio 1
	v_mfma_f32_16x16x32_bf16 v[118:121], v[162:165], v[178:181], v[118:121]
	v_mfma_f32_16x16x32_bf16 v[114:117], v[170:173], v[178:181], v[114:117]
	v_mfma_f32_16x16x32_bf16 v[102:105], v[162:165], v[186:189], v[102:105]
	v_mfma_f32_16x16x32_bf16 v[98:101], v[170:173], v[186:189], v[98:101]
	v_mfma_f32_16x16x32_bf16 v[86:89], v[162:165], v[204:207], v[86:89]
	v_mfma_f32_16x16x32_bf16 v[82:85], v[170:173], v[204:207], v[82:85]
	v_mfma_f32_16x16x32_bf16 v[70:73], v[162:165], v[212:215], v[70:73]
	v_mfma_f32_16x16x32_bf16 v[66:69], v[170:173], v[212:215], v[66:69]
	v_mfma_f32_16x16x32_bf16 v[118:121], v[166:169], v[182:185], v[118:121]
	v_mfma_f32_16x16x32_bf16 v[114:117], v[174:177], v[182:185], v[114:117]
	v_mfma_f32_16x16x32_bf16 v[102:105], v[166:169], v[190:193], v[102:105]
	v_mfma_f32_16x16x32_bf16 v[98:101], v[174:177], v[190:193], v[98:101]
	v_mfma_f32_16x16x32_bf16 v[86:89], v[166:169], v[208:211], v[86:89]
	v_mfma_f32_16x16x32_bf16 v[82:85], v[174:177], v[208:211], v[82:85]
	v_mfma_f32_16x16x32_bf16 v[70:73], v[166:169], v[216:219], v[70:73]
	v_mfma_f32_16x16x32_bf16 v[66:69], v[174:177], v[216:219], v[66:69]
	s_barrier
	s_setprio 0
	s_add_i32 s42, s42, s12
	s_mov_b32 m0, s42
	global_load_lds_dwordx4 v0, s[20:21]
	s_add_i32 m0, s42, 0x2000
	s_add_u32 s42, s20, 0x40000
	s_addc_u32 s43, s21, 0
	s_add_i32 s44, s44, s12
	global_load_lds_dwordx4 v130, s[20:21]
	s_mov_b32 m0, s44
	s_nop 0
	global_load_lds_dwordx4 v0, s[42:43]
	s_add_i32 m0, s44, 0x2000
	s_nop 0
	global_load_lds_dwordx4 v130, s[42:43]
	s_mov_b32 m0, s23
	s_nop 0
	global_load_lds_dwordx4 v134, s[60:61]
	s_mov_b32 m0, s24
	s_nop 0
	global_load_lds_dwordx4 v132, s[60:61]
	ds_read_b128 v[178:181], v145 offset:16384
	ds_read_b128 v[182:185], v145 offset:17408
	ds_read_b128 v[186:189], v145 offset:18432
	ds_read_b128 v[190:193], v145 offset:19456
	ds_read_b128 v[204:207], v145 offset:20480
	ds_read_b128 v[208:211], v145 offset:21504
	ds_read_b128 v[212:215], v145 offset:22528
	ds_read_b128 v[216:219], v145 offset:23552
	s_waitcnt vmcnt(8)
	s_waitcnt lgkmcnt(0)
	s_setprio 1
	s_barrier
	v_mfma_f32_16x16x32_bf16 v[62:65], v[146:149], v[178:181], v[62:65]
	v_mfma_f32_16x16x32_bf16 v[58:61], v[154:157], v[178:181], v[58:61]
	v_mfma_f32_16x16x32_bf16 v[46:49], v[146:149], v[186:189], v[46:49]
	v_mfma_f32_16x16x32_bf16 v[42:45], v[154:157], v[186:189], v[42:45]
	v_mfma_f32_16x16x32_bf16 v[30:33], v[146:149], v[204:207], v[30:33]
	v_mfma_f32_16x16x32_bf16 v[26:29], v[154:157], v[204:207], v[26:29]
	v_mfma_f32_16x16x32_bf16 v[14:17], v[146:149], v[212:215], v[14:17]
	v_mfma_f32_16x16x32_bf16 v[10:13], v[154:157], v[212:215], v[10:13]
	v_mfma_f32_16x16x32_bf16 v[62:65], v[150:153], v[182:185], v[62:65]
	v_mfma_f32_16x16x32_bf16 v[58:61], v[158:161], v[182:185], v[58:61]
	v_mfma_f32_16x16x32_bf16 v[46:49], v[150:153], v[190:193], v[46:49]
	v_mfma_f32_16x16x32_bf16 v[42:45], v[158:161], v[190:193], v[42:45]
	v_mfma_f32_16x16x32_bf16 v[30:33], v[150:153], v[208:211], v[30:33]
	v_mfma_f32_16x16x32_bf16 v[26:29], v[158:161], v[208:211], v[26:29]
	v_mfma_f32_16x16x32_bf16 v[14:17], v[150:153], v[216:219], v[14:17]
	v_mfma_f32_16x16x32_bf16 v[10:13], v[158:161], v[216:219], v[10:13]
	s_setprio 0
	s_setprio 1
	v_mfma_f32_16x16x32_bf16 v[54:57], v[162:165], v[178:181], v[54:57]
	v_mfma_f32_16x16x32_bf16 v[50:53], v[170:173], v[178:181], v[50:53]
	v_mfma_f32_16x16x32_bf16 v[38:41], v[162:165], v[186:189], v[38:41]
	v_mfma_f32_16x16x32_bf16 v[34:37], v[170:173], v[186:189], v[34:37]
	v_mfma_f32_16x16x32_bf16 v[22:25], v[162:165], v[204:207], v[22:25]
	v_mfma_f32_16x16x32_bf16 v[18:21], v[170:173], v[204:207], v[18:21]
	v_mfma_f32_16x16x32_bf16 v[6:9], v[162:165], v[212:215], v[6:9]
	v_mfma_f32_16x16x32_bf16 v[2:5], v[170:173], v[212:215], v[2:5]
	v_mfma_f32_16x16x32_bf16 v[54:57], v[166:169], v[182:185], v[54:57]
	v_mfma_f32_16x16x32_bf16 v[50:53], v[174:177], v[182:185], v[50:53]
	v_mfma_f32_16x16x32_bf16 v[38:41], v[166:169], v[190:193], v[38:41]
	v_mfma_f32_16x16x32_bf16 v[34:37], v[174:177], v[190:193], v[34:37]
	v_mfma_f32_16x16x32_bf16 v[22:25], v[166:169], v[208:211], v[22:25]
	v_mfma_f32_16x16x32_bf16 v[18:21], v[174:177], v[208:211], v[18:21]
	v_mfma_f32_16x16x32_bf16 v[6:9], v[166:169], v[216:219], v[6:9]
	v_mfma_f32_16x16x32_bf16 v[2:5], v[174:177], v[216:219], v[2:5]
	s_barrier
; #define PG8_STAGE(bufoff, gbase, voff) do { _Pragma("unroll") for (int _i = 0; _i < 2; ++_i) \
;         __builtin_amdgcn_global_load_lds((const gunsigned*)((const gchar*)(gbase) + (voff)[_i]), (LAS unsigned*)(lds + (bufoff) + ldsw + _i * 8192), 16, 0, 0); } while (0)
; #define PG8_LDA(dst, b, h) do { _Pragma("unroll") for (int m = 0; m < 4; ++m) _Pragma("unroll") for (int k = 0; k < 2; ++k) dst[m][k] = *(const LAS bf16x8*)(lds + PG8_SA(b, h) + aoff + m * 2048 + k * 1024); } while (0)
; #define PG8_LDB(dst, b, h) do { _Pragma("unroll") for (int n = 0; n < 2; ++n) _Pragma("unroll") for (int k = 0; k < 2; ++k) dst[n][k] = *(const LAS bf16x8*)(lds + PG8_SB(b, h) + boff + n * 2048 + k * 1024); } while (0)
; #define PG8_MMA(ai, bj, At, Bt) do { __builtin_amdgcn_s_setprio(1); _Pragma("unroll") for (int m = 0; m < 4; ++m) _Pragma("unroll") for (int n = 0; n < 2; ++n) _Pragma("unroll") for (int k = 0; k < 2; ++k) \
;         acc[ai][bj][m][n] = __builtin_amdgcn_mfma_f32_16x16x32_bf16(Bt[n][k], At[m][k], acc[ai][bj][m][n], 0, 0, 0); __builtin_amdgcn_s_setprio(0); } while (0)
; #define PG8_WAIT_V(n) asm volatile("s_waitcnt vmcnt(" #n ")" ::: "memory")
; #define PG8_WAIT_L(n) asm volatile("s_waitcnt lgkmcnt(" #n ")" ::: "memory")
; #define PG8_BAR __builtin_amdgcn_s_barrier()
; #define PG8_SCHED __builtin_amdgcn_sched_barrier(0)
; template <class Epi, class Sched>
; __device__ __forceinline__ void gemm_phase(LAS unsigned char* lds, const int tid, const Gemm g, const Sched& S, const Epi& E) {
;     ...
;             PG8_LDB(B0, 1, 0); PG8_LDB(B1, 1, 1); PG8_SCHED; PG8_LDA(At, 1, 0); PG8_STAGE(PG8_SA(0, 1), a2 + hstep, voffA);
;             PG8_WAIT_V(8); PG8_WAIT_L(0); PG8_BAR; PG8_MMA(0, 0, At, B0); PG8_MMA(0, 1, At, B1); PG8_BAR; PG8_SCHED;
;             PG8_LDA(At, 1, 1); PG8_STAGE(PG8_SB(1, 0), b3, voffB); PG8_STAGE(PG8_SB(1, 1), b3 + hstep, voffB); PG8_STAGE(PG8_SA(1, 0), a3, voffA);
;             PG8_WAIT_V(8); PG8_WAIT_L(0); PG8_BAR; PG8_MMA(1, 0, At, B0); PG8_MMA(1, 1, At, B1); PG8_BAR; PG8_SCHED;
;         }
;         if (wr == 0) PG8_BAR;
	s_setprio 0
	s_add_i32 s44, 0, 0x18000
	s_add_i32 s45, 0, 0x1c000
	s_add_u32 s42, s60, 0x40000
	s_addc_u32 s43, s61, 0
	s_mov_b32 m0, s29
	global_load_lds_dwordx4 v134, s[42:43]
	s_mov_b32 m0, s30
	s_nop 0
	global_load_lds_dwordx4 v132, s[42:43]
	v_add_u32_e32 v158, s44, v143
	v_add_u32_e32 v174, s45, v143
	ds_read_b128 v[146:149], v158
	ds_read_b128 v[150:153], v158 offset:1024
	ds_read_b128 v[154:157], v158 offset:2048
	ds_read_b128 v[158:161], v158 offset:3072
	ds_read_b128 v[162:165], v174
	ds_read_b128 v[166:169], v174 offset:1024
	ds_read_b128 v[170:173], v174 offset:2048
	ds_read_b128 v[174:177], v174 offset:3072
	ds_read_b128 v[178:181], v145 offset:32768
	ds_read_b128 v[182:185], v145 offset:33792
	ds_read_b128 v[186:189], v145 offset:34816
	ds_read_b128 v[190:193], v145 offset:35840
	ds_read_b128 v[204:207], v145 offset:36864
	ds_read_b128 v[208:211], v145 offset:37888
	ds_read_b128 v[212:215], v145 offset:38912
	ds_read_b128 v[216:219], v145 offset:39936
	s_waitcnt vmcnt(8)
	s_waitcnt lgkmcnt(0)
	s_setprio 1
	s_barrier
	v_mfma_f32_16x16x32_bf16 v[126:129], v[146:149], v[178:181], v[126:129]
	v_mfma_f32_16x16x32_bf16 v[122:125], v[154:157], v[178:181], v[122:125]
	v_mfma_f32_16x16x32_bf16 v[110:113], v[146:149], v[186:189], v[110:113]
	v_mfma_f32_16x16x32_bf16 v[106:109], v[154:157], v[186:189], v[106:109]
	v_mfma_f32_16x16x32_bf16 v[94:97], v[146:149], v[204:207], v[94:97]
	v_mfma_f32_16x16x32_bf16 v[90:93], v[154:157], v[204:207], v[90:93]
	v_mfma_f32_16x16x32_bf16 v[78:81], v[146:149], v[212:215], v[78:81]
	v_mfma_f32_16x16x32_bf16 v[74:77], v[154:157], v[212:215], v[74:77]
	v_mfma_f32_16x16x32_bf16 v[126:129], v[150:153], v[182:185], v[126:129]
	v_mfma_f32_16x16x32_bf16 v[122:125], v[158:161], v[182:185], v[122:125]
	v_mfma_f32_16x16x32_bf16 v[110:113], v[150:153], v[190:193], v[110:113]
	v_mfma_f32_16x16x32_bf16 v[106:109], v[158:161], v[190:193], v[106:109]
	v_mfma_f32_16x16x32_bf16 v[94:97], v[150:153], v[208:211], v[94:97]
	v_mfma_f32_16x16x32_bf16 v[90:93], v[158:161], v[208:211], v[90:93]
	v_mfma_f32_16x16x32_bf16 v[78:81], v[150:153], v[216:219], v[78:81]
	v_mfma_f32_16x16x32_bf16 v[74:77], v[158:161], v[216:219], v[74:77]
	s_setprio 0
	s_setprio 1
	v_mfma_f32_16x16x32_bf16 v[118:121], v[162:165], v[178:181], v[118:121]
	v_mfma_f32_16x16x32_bf16 v[114:117], v[170:173], v[178:181], v[114:117]
	v_mfma_f32_16x16x32_bf16 v[102:105], v[162:165], v[186:189], v[102:105]
	v_mfma_f32_16x16x32_bf16 v[98:101], v[170:173], v[186:189], v[98:101]
	v_mfma_f32_16x16x32_bf16 v[86:89], v[162:165], v[204:207], v[86:89]
	v_mfma_f32_16x16x32_bf16 v[82:85], v[170:173], v[204:207], v[82:85]
	v_mfma_f32_16x16x32_bf16 v[70:73], v[162:165], v[212:215], v[70:73]
	v_mfma_f32_16x16x32_bf16 v[66:69], v[170:173], v[212:215], v[66:69]
	v_mfma_f32_16x16x32_bf16 v[118:121], v[166:169], v[182:185], v[118:121]
	v_mfma_f32_16x16x32_bf16 v[114:117], v[174:177], v[182:185], v[114:117]
	v_mfma_f32_16x16x32_bf16 v[102:105], v[166:169], v[190:193], v[102:105]
	v_mfma_f32_16x16x32_bf16 v[98:101], v[174:177], v[190:193], v[98:101]
	v_mfma_f32_16x16x32_bf16 v[86:89], v[166:169], v[208:211], v[86:89]
	v_mfma_f32_16x16x32_bf16 v[82:85], v[174:177], v[208:211], v[82:85]
	v_mfma_f32_16x16x32_bf16 v[70:73], v[166:169], v[216:219], v[70:73]
	v_mfma_f32_16x16x32_bf16 v[66:69], v[174:177], v[216:219], v[66:69]
	s_barrier
	s_setprio 0
	s_add_i32 s42, s44, s12
	s_mov_b32 m0, s42
	ds_read_b128 v[178:181], v145 offset:49152
	global_load_lds_dwordx4 v141, s[20:21]
	s_add_i32 m0, s42, 0x2000
	s_add_i32 s42, s45, s12
	global_load_lds_dwordx4 v195, s[20:21]
	s_add_u32 s20, s20, 0x40080
	s_addc_u32 s21, s21, 0
	s_mov_b32 m0, s42
	s_nop 0
	global_load_lds_dwordx4 v0, s[20:21]
	s_add_i32 m0, s42, 0x2000
	s_nop 0
	global_load_lds_dwordx4 v130, s[20:21]
	s_mov_b32 m0, s31
	s_nop 0
	global_load_lds_dwordx4 v221, s[60:61]
	s_mov_b32 m0, s34
	s_nop 0
	global_load_lds_dwordx4 v223, s[60:61]
	ds_read_b128 v[182:185], v145 offset:50176
	ds_read_b128 v[186:189], v145 offset:51200
	ds_read_b128 v[190:193], v145 offset:52224
	ds_read_b128 v[204:207], v145 offset:53248
	ds_read_b128 v[208:211], v145 offset:54272
	ds_read_b128 v[212:215], v145 offset:55296
	ds_read_b128 v[216:219], v145 offset:56320
	s_waitcnt vmcnt(8)
	s_waitcnt lgkmcnt(0)
	s_setprio 1
	s_barrier
	v_mfma_f32_16x16x32_bf16 v[62:65], v[146:149], v[178:181], v[62:65]
	v_mfma_f32_16x16x32_bf16 v[58:61], v[154:157], v[178:181], v[58:61]
	v_mfma_f32_16x16x32_bf16 v[46:49], v[146:149], v[186:189], v[46:49]
	v_mfma_f32_16x16x32_bf16 v[42:45], v[154:157], v[186:189], v[42:45]
	v_mfma_f32_16x16x32_bf16 v[30:33], v[146:149], v[204:207], v[30:33]
	v_mfma_f32_16x16x32_bf16 v[26:29], v[154:157], v[204:207], v[26:29]
	v_mfma_f32_16x16x32_bf16 v[14:17], v[146:149], v[212:215], v[14:17]
	v_mfma_f32_16x16x32_bf16 v[10:13], v[154:157], v[212:215], v[10:13]
	v_mfma_f32_16x16x32_bf16 v[62:65], v[150:153], v[182:185], v[62:65]
	v_mfma_f32_16x16x32_bf16 v[58:61], v[158:161], v[182:185], v[58:61]
	v_mfma_f32_16x16x32_bf16 v[46:49], v[150:153], v[190:193], v[46:49]
	v_mfma_f32_16x16x32_bf16 v[42:45], v[158:161], v[190:193], v[42:45]
	v_mfma_f32_16x16x32_bf16 v[30:33], v[150:153], v[208:211], v[30:33]
	v_mfma_f32_16x16x32_bf16 v[26:29], v[158:161], v[208:211], v[26:29]
	v_mfma_f32_16x16x32_bf16 v[14:17], v[150:153], v[216:219], v[14:17]
	v_mfma_f32_16x16x32_bf16 v[10:13], v[158:161], v[216:219], v[10:13]
	s_setprio 0
	s_setprio 1
	v_mfma_f32_16x16x32_bf16 v[54:57], v[162:165], v[178:181], v[54:57]
	v_mfma_f32_16x16x32_bf16 v[50:53], v[170:173], v[178:181], v[50:53]
	v_mfma_f32_16x16x32_bf16 v[38:41], v[162:165], v[186:189], v[38:41]
	v_mfma_f32_16x16x32_bf16 v[34:37], v[170:173], v[186:189], v[34:37]
	v_mfma_f32_16x16x32_bf16 v[22:25], v[162:165], v[204:207], v[22:25]
	v_mfma_f32_16x16x32_bf16 v[18:21], v[170:173], v[204:207], v[18:21]
	v_mfma_f32_16x16x32_bf16 v[6:9], v[162:165], v[212:215], v[6:9]
	v_mfma_f32_16x16x32_bf16 v[2:5], v[170:173], v[212:215], v[2:5]
	v_mfma_f32_16x16x32_bf16 v[54:57], v[166:169], v[182:185], v[54:57]
	v_mfma_f32_16x16x32_bf16 v[50:53], v[174:177], v[182:185], v[50:53]
	v_mfma_f32_16x16x32_bf16 v[38:41], v[166:169], v[190:193], v[38:41]
	v_mfma_f32_16x16x32_bf16 v[34:37], v[174:177], v[190:193], v[34:37]
	v_mfma_f32_16x16x32_bf16 v[22:25], v[166:169], v[208:211], v[22:25]
	v_mfma_f32_16x16x32_bf16 v[18:21], v[174:177], v[208:211], v[18:21]
	v_mfma_f32_16x16x32_bf16 v[6:9], v[166:169], v[216:219], v[6:9]
	v_mfma_f32_16x16x32_bf16 v[2:5], v[174:177], v[216:219], v[2:5]
	s_barrier
	s_setprio 0
	s_add_i32 s41, s41, 2
	s_add_u32 s39, s39, 0x100
	s_addc_u32 s40, s40, 0
	s_add_u32 s58, s58, 0x100
	s_addc_u32 s59, s59, 0
	s_cmp_gt_u32 s41, 13
	s_cbranch_scc0 .LBB0_647
	s_and_b64 vcc, exec, s[4:5]
	s_cbranch_vccz .LBB0_650
	s_barrier
